# saddr LDS-DMA + peeled relaxed-wait first iteration, setprio toggles kept
# baseline (speedup 1.0000x reference)
; #define PG8_STAGE(bufoff, gbase, voff) do { _Pragma("unroll") for (int _i = 0; _i < 2; ++_i) \
;         __builtin_amdgcn_global_load_lds((const unsigned*)((const char*)(gbase) + (voff)[_i]), (LAS unsigned*)(lds + (bufoff) + ldsw + _i * 8192), 16, 0, 0); } while (0)
; #define PG8_LDA(dst, b, h) do { _Pragma("unroll") for (int m = 0; m < 4; ++m) _Pragma("unroll") for (int k = 0; k < 2; ++k) dst[m][k] = *(const LAS bf16x8*)(lds + PG8_SA(b, h) + aoff + m * 2048 + k * 1024); } while (0)
; #define PG8_LDB(dst, b, h) do { _Pragma("unroll") for (int n = 0; n < 2; ++n) _Pragma("unroll") for (int k = 0; k < 2; ++k) dst[n][k] = *(const LAS bf16x8*)(lds + PG8_SB(b, h) + boff + n * 2048 + k * 1024); } while (0)
; #define PG8_WAIT_V(n) asm volatile("s_waitcnt vmcnt(" #n ")" ::: "memory")
; #define PG8_WAIT_L(n) asm volatile("s_waitcnt lgkmcnt(" #n ")" ::: "memory")
; #define PG8_BAR __builtin_amdgcn_s_barrier()
; template <class Epi, class Sched, int KC, bool ALIGN_EPI = false, bool SP2 = false, bool ATILED = false>
; __device__ __forceinline__ void gemm_phase(LAS unsigned char* lds, const Gemm g, const Sched& S, const Epi& E, int wave_s) {
;     ...
;         const bool has_next = S.next(ui + 1, nxt);
;         const char* nA = has_next ? (const char*)g.A + (size_t)nxt.pm * tstepA : cA; const char* nB = has_next ? (const char*)g.Bt + (size_t)nxt.pn * tstep : cB;
;         for (int t = 0; t < nt; t += 2) {
;             const bool last = (t == nt - 2);
;             const char* a1 = cA + PG8_AOFF(t + 1);
;             const char* a2 = last ? nA : cA + PG8_AOFF(t + 2); const char* b2 = last ? nB : cB + (size_t)(t + 2) * kstep;
;             const char* a3 = a2 + kstep; const char* b3 = b2 + kstep;
;             if (last && has_next) S.a_ready(nxt);
;             if constexpr (SP2) {
;             PG8_LDB(B0, 0, 0); PG8_LDB(B1, 0, 1); PG8_SCHED; PG8_LDA(At, 0, 0); PG8_STAGE(PG8_SA(1, 1), a1 + hstepA, voffA);
;             PG8_WAIT_V(8); PG8_WAIT_L(0); PG8_BAR; PG8_MMA(0, 0, At, B0); PG8_MMA(0, 1, At, B1); PG8_BAR; PG8_SCHED;
;     ...
; #pragma unroll
;         for (int a = 0; a < 2; ++a)
; #pragma unroll
;             for (int b = 0; b < 2; ++b)
; #pragma unroll
;                 for (int m = 0; m < 4; ++m)
; #pragma unroll
;                     for (int n = 0; n < 2; ++n) acc[a][b][m][n] = (f32x4){0.f, 0.f, 0.f, 0.f};
;         cur = nxt; cA = nA; cB = nB; ++ui;
.LBB0_232:
	s_ashr_i32 s19, s18, 31
	s_lshl_b64 s[20:21], s[18:19], 17
	s_add_u32 s20, s39, s20
	s_addc_u32 s21, s40, s21
	s_and_b64 s[22:23], s[6:7], exec
	s_cselect_b32 s19, s21, s27
	s_cselect_b32 s53, s20, s26
	s_ashr_i32 s17, s16, 31
	s_lshl_b64 s[22:23], s[16:17], 20
	s_add_u32 s22, s41, s22
	s_addc_u32 s23, s42, s23
	s_and_b64 s[30:31], s[6:7], exec
	s_cselect_b32 s17, s23, s29
	s_cselect_b32 s54, s22, s28
	s_add_u32 s55, s28, 0x100
	v_mov_b32_e32 v2, 0
	s_addc_u32 s56, s29, 0
	s_mov_b32 s57, -2
	s_mov_b64 s[28:29], 0
	s_mov_b32 s58, 0x400000
	v_mov_b32_e32 v3, v2
	v_mov_b32_e32 v4, v2
	v_mov_b32_e32 v5, v2
	v_mov_b32_e32 v14, v2
	v_mov_b32_e32 v15, v2
	v_mov_b32_e32 v16, v2
	v_mov_b32_e32 v17, v2
	v_mov_b32_e32 v22, v2
	v_mov_b32_e32 v23, v2
	v_mov_b32_e32 v24, v2
	v_mov_b32_e32 v25, v2
	v_mov_b32_e32 v30, v2
	v_mov_b32_e32 v31, v2
	v_mov_b32_e32 v32, v2
	v_mov_b32_e32 v33, v2
	v_mov_b32_e32 v38, v2
	v_mov_b32_e32 v39, v2
	v_mov_b32_e32 v40, v2
	v_mov_b32_e32 v41, v2
	v_mov_b32_e32 v46, v2
	v_mov_b32_e32 v47, v2
	v_mov_b32_e32 v48, v2
	v_mov_b32_e32 v49, v2
	v_mov_b32_e32 v54, v2
	v_mov_b32_e32 v55, v2
	v_mov_b32_e32 v56, v2
	v_mov_b32_e32 v57, v2
	v_mov_b32_e32 v62, v2
	v_mov_b32_e32 v63, v2
	v_mov_b32_e32 v64, v2
	v_mov_b32_e32 v65, v2
	v_mov_b32_e32 v6, v2
	v_mov_b32_e32 v7, v2
	v_mov_b32_e32 v8, v2
	v_mov_b32_e32 v9, v2
	v_mov_b32_e32 v10, v2
	v_mov_b32_e32 v11, v2
	v_mov_b32_e32 v12, v2
	v_mov_b32_e32 v13, v2
	v_mov_b32_e32 v18, v2
	v_mov_b32_e32 v19, v2
	v_mov_b32_e32 v20, v2
	v_mov_b32_e32 v21, v2
	v_mov_b32_e32 v26, v2
	v_mov_b32_e32 v27, v2
	v_mov_b32_e32 v28, v2
	v_mov_b32_e32 v29, v2
	v_mov_b32_e32 v34, v2
	v_mov_b32_e32 v35, v2
	v_mov_b32_e32 v36, v2
	v_mov_b32_e32 v37, v2
	v_mov_b32_e32 v42, v2
	v_mov_b32_e32 v43, v2
	v_mov_b32_e32 v44, v2
	v_mov_b32_e32 v45, v2
	v_mov_b32_e32 v50, v2
	v_mov_b32_e32 v51, v2
	v_mov_b32_e32 v52, v2
	v_mov_b32_e32 v53, v2
	v_mov_b32_e32 v58, v2
	v_mov_b32_e32 v59, v2
	v_mov_b32_e32 v60, v2
	v_mov_b32_e32 v61, v2
	v_mov_b32_e32 v70, v2
	v_mov_b32_e32 v71, v2
	v_mov_b32_e32 v72, v2
	v_mov_b32_e32 v73, v2
	v_mov_b32_e32 v78, v2
	v_mov_b32_e32 v79, v2
	v_mov_b32_e32 v80, v2
	v_mov_b32_e32 v81, v2
	v_mov_b32_e32 v86, v2
	v_mov_b32_e32 v87, v2
	v_mov_b32_e32 v88, v2
	v_mov_b32_e32 v89, v2
	v_mov_b32_e32 v94, v2
	v_mov_b32_e32 v95, v2
	v_mov_b32_e32 v96, v2
	v_mov_b32_e32 v97, v2
	v_mov_b32_e32 v102, v2
	v_mov_b32_e32 v103, v2
	v_mov_b32_e32 v104, v2
	v_mov_b32_e32 v105, v2
	v_mov_b32_e32 v110, v2
	v_mov_b32_e32 v111, v2
	v_mov_b32_e32 v112, v2
	v_mov_b32_e32 v113, v2
	v_mov_b32_e32 v118, v2
	v_mov_b32_e32 v119, v2
	v_mov_b32_e32 v120, v2
	v_mov_b32_e32 v121, v2
	v_mov_b32_e32 v126, v2
	v_mov_b32_e32 v127, v2
	v_mov_b32_e32 v128, v2
	v_mov_b32_e32 v129, v2
	v_mov_b32_e32 v66, v2
	v_mov_b32_e32 v67, v2
	v_mov_b32_e32 v68, v2
	v_mov_b32_e32 v69, v2
	v_mov_b32_e32 v74, v2
	v_mov_b32_e32 v75, v2
	v_mov_b32_e32 v76, v2
	v_mov_b32_e32 v77, v2
	v_mov_b32_e32 v82, v2
	v_mov_b32_e32 v83, v2
	v_mov_b32_e32 v84, v2
	v_mov_b32_e32 v85, v2
	v_mov_b32_e32 v90, v2
	v_mov_b32_e32 v91, v2
	v_mov_b32_e32 v92, v2
	v_mov_b32_e32 v93, v2
	v_mov_b32_e32 v98, v2
	v_mov_b32_e32 v99, v2
	v_mov_b32_e32 v100, v2
	v_mov_b32_e32 v101, v2
	v_mov_b32_e32 v106, v2
	v_mov_b32_e32 v107, v2
	v_mov_b32_e32 v108, v2
	v_mov_b32_e32 v109, v2
	v_mov_b32_e32 v114, v2
	v_mov_b32_e32 v115, v2
	v_mov_b32_e32 v116, v2
	v_mov_b32_e32 v117, v2
	v_mov_b32_e32 v122, v2
	v_mov_b32_e32 v123, v2
	v_mov_b32_e32 v124, v2
	v_mov_b32_e32 v125, v2
	s_add_i32 s30, s58, 0xffc00000
	s_and_b32 s30, s30, 0x3800000
	s_and_b32 s31, s28, 0x100
	s_or_b32 s59, s31, s30
	s_and_b32 s34, s58, 0x7800000
	s_add_u32 s30, s28, 0x100
	s_addc_u32 s31, s29, 0
	s_and_b32 s35, s30, 0x100
	s_or_b32 s34, s34, s35
	s_add_u32 s34, s26, s34
	s_addc_u32 s35, s27, 0
	s_add_u32 s28, s55, s28
	s_addc_u32 s29, s56, s29
	s_add_i32 s62, 0, 0x10000
	s_cmp_eq_u32 s57, 28
	s_cselect_b32 s35, s19, s35
	s_cselect_b32 s34, s53, s34
	v_add_u32_e32 v139, s62, v163
	s_cselect_b32 s29, s17, s29
	s_cselect_b32 s28, s54, s28
	s_add_i32 s63, 0, 0x14000
	ds_read_b128 v[152:155], v139
	ds_read_b128 v[156:159], v139 offset:1024
	ds_read_b128 v[168:171], v139 offset:2048
	ds_read_b128 v[172:175], v139 offset:3072
	v_add_u32_e32 v139, s63, v163
	ds_read_b128 v[176:179], v139
	ds_read_b128 v[180:183], v139 offset:1024
	ds_read_b128 v[184:187], v139 offset:2048
	ds_read_b128 v[188:191], v139 offset:3072
	s_add_u32 s59, s26, s59
	s_addc_u32 s61, s27, 0
	s_add_u32 s60, s59, 0x10080
	s_addc_u32 s61, s61, 0
	s_add_i32 m0, s44, 0xc000
	ds_read_b128 v[198:201], v166
	ds_read_b128 v[202:205], v166 offset:1024
	ds_read_b128 v[206:209], v166 offset:2048
	ds_read_b128 v[210:213], v166 offset:3072
	ds_read_b128 v[214:217], v166 offset:4096
	ds_read_b128 v[218:221], v166 offset:5120
	ds_read_b128 v[222:225], v166 offset:6144
	ds_read_b128 v[226:229], v166 offset:7168
	global_load_lds_dwordx4 v136, s[60:61]
	s_add_i32 m0, s44, 0xe000
	s_nop 0
	global_load_lds_dwordx4 v132, s[60:61]
	s_waitcnt vmcnt(16)
	s_waitcnt lgkmcnt(0)
	s_barrier
; #define PG8_STAGE(bufoff, gbase, voff) do { _Pragma("unroll") for (int _i = 0; _i < 2; ++_i) \
;         __builtin_amdgcn_global_load_lds((const unsigned*)((const char*)(gbase) + (voff)[_i]), (LAS unsigned*)(lds + (bufoff) + ldsw + _i * 8192), 16, 0, 0); } while (0)
; #define PG8_LDA(dst, b, h) do { _Pragma("unroll") for (int m = 0; m < 4; ++m) _Pragma("unroll") for (int k = 0; k < 2; ++k) dst[m][k] = *(const LAS bf16x8*)(lds + PG8_SA(b, h) + aoff + m * 2048 + k * 1024); } while (0)
; #define PG8_LDB(dst, b, h) do { _Pragma("unroll") for (int n = 0; n < 2; ++n) _Pragma("unroll") for (int k = 0; k < 2; ++k) dst[n][k] = *(const LAS bf16x8*)(lds + PG8_SB(b, h) + boff + n * 2048 + k * 1024); } while (0)
; #define PG8_MMA(ai, bj, At, Bt) do { __builtin_amdgcn_s_setprio(1); _Pragma("unroll") for (int m = 0; m < 4; ++m) _Pragma("unroll") for (int n = 0; n < 2; ++n) _Pragma("unroll") for (int k = 0; k < 2; ++k) \
;         acc[ai][bj][m][n] = __builtin_amdgcn_mfma_f32_16x16x32_bf16(Bt[n][k], At[m][k], acc[ai][bj][m][n], 0, 0, 0); __builtin_amdgcn_s_setprio(0); } while (0)
; #define PG8_WAIT_V(n) asm volatile("s_waitcnt vmcnt(" #n ")" ::: "memory")
; #define PG8_WAIT_L(n) asm volatile("s_waitcnt lgkmcnt(" #n ")" ::: "memory")
; #define PG8_BAR __builtin_amdgcn_s_barrier()
; #define PG8_SCHED __builtin_amdgcn_sched_barrier(0)
; template <class Epi, class Sched, int KC, bool ALIGN_EPI = false, bool SP2 = false, bool ATILED = false>
; __device__ __forceinline__ void gemm_phase(LAS unsigned char* lds, const Gemm g, const Sched& S, const Epi& E, int wave_s) {
;     ...
;             PG8_LDB(B0, 0, 0); PG8_LDB(B1, 0, 1); PG8_SCHED; PG8_LDA(At, 0, 0); PG8_STAGE(PG8_SA(1, 1), a1 + hstepA, voffA);
;             PG8_WAIT_V(8); PG8_WAIT_L(0); PG8_BAR; PG8_MMA(0, 0, At, B0); PG8_MMA(0, 1, At, B1); PG8_BAR; PG8_SCHED;
;             PG8_LDA(At, 0, 1); PG8_STAGE(PG8_SB(0, 0), b2, voffB); PG8_STAGE(PG8_SB(0, 1), b2 + hstepB, voffB); PG8_STAGE(PG8_SA(0, 0), a2, voffA);
;             PG8_WAIT_V(8); PG8_WAIT_L(0); PG8_BAR; PG8_MMA(1, 0, At, B0); PG8_MMA(1, 1, At, B1); PG8_BAR; PG8_SCHED;
	s_setprio 1
	s_waitcnt lgkmcnt(0)
	v_mfma_f32_16x16x32_bf16 v[122:125], v[152:155], v[198:201], v[122:125]
	v_mfma_f32_16x16x32_bf16 v[114:117], v[168:171], v[198:201], v[114:117]
	v_mfma_f32_16x16x32_bf16 v[106:109], v[152:155], v[206:209], v[106:109]
	v_mfma_f32_16x16x32_bf16 v[98:101], v[168:171], v[206:209], v[98:101]
	v_mfma_f32_16x16x32_bf16 v[90:93], v[152:155], v[214:217], v[90:93]
	v_mfma_f32_16x16x32_bf16 v[82:85], v[168:171], v[214:217], v[82:85]
	v_mfma_f32_16x16x32_bf16 v[74:77], v[152:155], v[222:225], v[74:77]
	v_mfma_f32_16x16x32_bf16 v[66:69], v[168:171], v[222:225], v[66:69]
	v_mfma_f32_16x16x32_bf16 v[122:125], v[156:159], v[202:205], v[122:125]
	v_mfma_f32_16x16x32_bf16 v[114:117], v[172:175], v[202:205], v[114:117]
	v_mfma_f32_16x16x32_bf16 v[106:109], v[156:159], v[210:213], v[106:109]
	v_mfma_f32_16x16x32_bf16 v[98:101], v[172:175], v[210:213], v[98:101]
	v_mfma_f32_16x16x32_bf16 v[90:93], v[156:159], v[218:221], v[90:93]
	v_mfma_f32_16x16x32_bf16 v[82:85], v[172:175], v[218:221], v[82:85]
	v_mfma_f32_16x16x32_bf16 v[74:77], v[156:159], v[226:229], v[74:77]
	v_mfma_f32_16x16x32_bf16 v[66:69], v[172:175], v[226:229], v[66:69]
	s_setprio 0
	s_setprio 1
	v_mfma_f32_16x16x32_bf16 v[126:129], v[176:179], v[198:201], v[126:129]
	v_mfma_f32_16x16x32_bf16 v[118:121], v[184:187], v[198:201], v[118:121]
	v_mfma_f32_16x16x32_bf16 v[110:113], v[176:179], v[206:209], v[110:113]
	v_mfma_f32_16x16x32_bf16 v[102:105], v[184:187], v[206:209], v[102:105]
	v_mfma_f32_16x16x32_bf16 v[94:97], v[176:179], v[214:217], v[94:97]
	v_mfma_f32_16x16x32_bf16 v[86:89], v[184:187], v[214:217], v[86:89]
	v_mfma_f32_16x16x32_bf16 v[78:81], v[176:179], v[222:225], v[78:81]
	v_mfma_f32_16x16x32_bf16 v[70:73], v[184:187], v[222:225], v[70:73]
	v_mfma_f32_16x16x32_bf16 v[126:129], v[180:183], v[202:205], v[126:129]
	v_mfma_f32_16x16x32_bf16 v[118:121], v[188:191], v[202:205], v[118:121]
	v_mfma_f32_16x16x32_bf16 v[110:113], v[180:183], v[210:213], v[110:113]
	v_mfma_f32_16x16x32_bf16 v[102:105], v[188:191], v[210:213], v[102:105]
	v_mfma_f32_16x16x32_bf16 v[94:97], v[180:183], v[218:221], v[94:97]
	v_mfma_f32_16x16x32_bf16 v[86:89], v[188:191], v[218:221], v[86:89]
	v_mfma_f32_16x16x32_bf16 v[78:81], v[180:183], v[226:229], v[78:81]
	v_mfma_f32_16x16x32_bf16 v[70:73], v[188:191], v[226:229], v[70:73]
	s_setprio 0
	s_barrier
	s_add_u32 s100, s34, 0x80
	s_addc_u32 s101, s35, 0
	s_add_i32 s59, s62, s38
	s_mov_b32 m0, s59
	ds_read_b128 v[198:201], v166 offset:16384
	ds_read_b128 v[202:205], v166 offset:17408
	ds_read_b128 v[206:209], v166 offset:18432
	ds_read_b128 v[210:213], v166 offset:19456
	ds_read_b128 v[214:217], v166 offset:20480
	ds_read_b128 v[218:221], v166 offset:21504
	ds_read_b128 v[222:225], v166 offset:22528
	ds_read_b128 v[226:229], v166 offset:23552
	global_load_lds_dwordx4 v134, s[28:29]
	s_add_i32 m0, s59, 0x2000
	s_add_u32 s60, s28, 0x80000
	s_addc_u32 s61, s29, 0
	s_add_i32 s59, s63, s38
	global_load_lds_dwordx4 v130, s[28:29]
	s_mov_b32 m0, s59
	s_nop 0
	global_load_lds_dwordx4 v134, s[60:61]
	s_add_i32 m0, s59, 0x2000
	s_nop 0
	global_load_lds_dwordx4 v130, s[60:61]
	s_mov_b32 m0, s44
	s_nop 0
	global_load_lds_dwordx4 v136, s[34:35]
	s_mov_b32 m0, s45
	s_nop 0
	global_load_lds_dwordx4 v132, s[34:35]
	s_waitcnt vmcnt(16)
	s_waitcnt lgkmcnt(0)
	s_barrier
	s_setprio 1
	s_waitcnt lgkmcnt(0)
	v_mfma_f32_16x16x32_bf16 v[58:61], v[152:155], v[198:201], v[58:61]
	v_mfma_f32_16x16x32_bf16 v[50:53], v[168:171], v[198:201], v[50:53]
	v_mfma_f32_16x16x32_bf16 v[42:45], v[152:155], v[206:209], v[42:45]
	v_mfma_f32_16x16x32_bf16 v[34:37], v[168:171], v[206:209], v[34:37]
	v_mfma_f32_16x16x32_bf16 v[26:29], v[152:155], v[214:217], v[26:29]
	v_mfma_f32_16x16x32_bf16 v[18:21], v[168:171], v[214:217], v[18:21]
	v_mfma_f32_16x16x32_bf16 v[10:13], v[152:155], v[222:225], v[10:13]
	v_mfma_f32_16x16x32_bf16 v[6:9], v[168:171], v[222:225], v[6:9]
	v_mfma_f32_16x16x32_bf16 v[58:61], v[156:159], v[202:205], v[58:61]
	v_mfma_f32_16x16x32_bf16 v[50:53], v[172:175], v[202:205], v[50:53]
	v_mfma_f32_16x16x32_bf16 v[42:45], v[156:159], v[210:213], v[42:45]
	v_mfma_f32_16x16x32_bf16 v[34:37], v[172:175], v[210:213], v[34:37]
	v_mfma_f32_16x16x32_bf16 v[26:29], v[156:159], v[218:221], v[26:29]
	v_mfma_f32_16x16x32_bf16 v[18:21], v[172:175], v[218:221], v[18:21]
	v_mfma_f32_16x16x32_bf16 v[10:13], v[156:159], v[226:229], v[10:13]
	v_mfma_f32_16x16x32_bf16 v[6:9], v[172:175], v[226:229], v[6:9]
	s_setprio 0
	s_setprio 1
	v_mfma_f32_16x16x32_bf16 v[62:65], v[176:179], v[198:201], v[62:65]
	v_mfma_f32_16x16x32_bf16 v[54:57], v[184:187], v[198:201], v[54:57]
	v_mfma_f32_16x16x32_bf16 v[46:49], v[176:179], v[206:209], v[46:49]
	v_mfma_f32_16x16x32_bf16 v[38:41], v[184:187], v[206:209], v[38:41]
	v_mfma_f32_16x16x32_bf16 v[30:33], v[176:179], v[214:217], v[30:33]
	v_mfma_f32_16x16x32_bf16 v[22:25], v[184:187], v[214:217], v[22:25]
	v_mfma_f32_16x16x32_bf16 v[14:17], v[176:179], v[222:225], v[14:17]
	v_mfma_f32_16x16x32_bf16 v[2:5], v[184:187], v[222:225], v[2:5]
	v_mfma_f32_16x16x32_bf16 v[62:65], v[180:183], v[202:205], v[62:65]
	v_mfma_f32_16x16x32_bf16 v[54:57], v[188:191], v[202:205], v[54:57]
	v_mfma_f32_16x16x32_bf16 v[46:49], v[180:183], v[210:213], v[46:49]
	v_mfma_f32_16x16x32_bf16 v[38:41], v[188:191], v[210:213], v[38:41]
	v_mfma_f32_16x16x32_bf16 v[30:33], v[180:183], v[218:221], v[30:33]
	v_mfma_f32_16x16x32_bf16 v[22:25], v[188:191], v[218:221], v[22:25]
	v_mfma_f32_16x16x32_bf16 v[14:17], v[180:183], v[226:229], v[14:17]
	v_mfma_f32_16x16x32_bf16 v[2:5], v[188:191], v[226:229], v[2:5]
	s_setprio 0
	s_barrier
; #define PG8_STAGE(bufoff, gbase, voff) do { _Pragma("unroll") for (int _i = 0; _i < 2; ++_i) \
;         __builtin_amdgcn_global_load_lds((const unsigned*)((const char*)(gbase) + (voff)[_i]), (LAS unsigned*)(lds + (bufoff) + ldsw + _i * 8192), 16, 0, 0); } while (0)
; #define PG8_LDA(dst, b, h) do { _Pragma("unroll") for (int m = 0; m < 4; ++m) _Pragma("unroll") for (int k = 0; k < 2; ++k) dst[m][k] = *(const LAS bf16x8*)(lds + PG8_SA(b, h) + aoff + m * 2048 + k * 1024); } while (0)
; #define PG8_LDB(dst, b, h) do { _Pragma("unroll") for (int n = 0; n < 2; ++n) _Pragma("unroll") for (int k = 0; k < 2; ++k) dst[n][k] = *(const LAS bf16x8*)(lds + PG8_SB(b, h) + boff + n * 2048 + k * 1024); } while (0)
; #define PG8_MMA(ai, bj, At, Bt) do { __builtin_amdgcn_s_setprio(1); _Pragma("unroll") for (int m = 0; m < 4; ++m) _Pragma("unroll") for (int n = 0; n < 2; ++n) _Pragma("unroll") for (int k = 0; k < 2; ++k) \
;         acc[ai][bj][m][n] = __builtin_amdgcn_mfma_f32_16x16x32_bf16(Bt[n][k], At[m][k], acc[ai][bj][m][n], 0, 0, 0); __builtin_amdgcn_s_setprio(0); } while (0)
; #define PG8_WAIT_V(n) asm volatile("s_waitcnt vmcnt(" #n ")" ::: "memory")
; #define PG8_WAIT_L(n) asm volatile("s_waitcnt lgkmcnt(" #n ")" ::: "memory")
; #define PG8_BAR __builtin_amdgcn_s_barrier()
; #define PG8_SCHED __builtin_amdgcn_sched_barrier(0)
; template <class Epi, class Sched, int KC, bool ALIGN_EPI = false, bool SP2 = false, bool ATILED = false>
; __device__ __forceinline__ void gemm_phase(LAS unsigned char* lds, const Gemm g, const Sched& S, const Epi& E, int wave_s) {
;     ...
;             PG8_LDB(B0, 1, 0); PG8_LDB(B1, 1, 1); PG8_SCHED; PG8_LDA(At, 1, 0); PG8_STAGE(PG8_SA(0, 1), a2 + hstepA, voffA);
;             PG8_WAIT_V(8); PG8_WAIT_L(0); PG8_BAR; PG8_MMA(0, 0, At, B0); PG8_MMA(0, 1, At, B1); PG8_BAR; PG8_SCHED;
;             PG8_LDA(At, 1, 1); PG8_STAGE(PG8_SB(1, 0), b3, voffB); PG8_STAGE(PG8_SB(1, 1), b3 + hstepB, voffB); PG8_STAGE(PG8_SA(1, 0), a3, voffA);
;             PG8_WAIT_V(8); PG8_WAIT_L(0); PG8_BAR; PG8_MMA(1, 0, At, B0); PG8_MMA(1, 1, At, B1); PG8_BAR; PG8_SCHED;
	s_add_i32 s59, 0, 0x18000
	v_add_u32_e32 v139, s59, v163
	s_add_i32 s60, 0, 0x1c000
	ds_read_b128 v[152:155], v139
	ds_read_b128 v[156:159], v139 offset:1024
	ds_read_b128 v[168:171], v139 offset:2048
	ds_read_b128 v[172:175], v139 offset:3072
	v_add_u32_e32 v139, s60, v163
	ds_read_b128 v[176:179], v139
	ds_read_b128 v[180:183], v139 offset:1024
	ds_read_b128 v[184:187], v139 offset:2048
	ds_read_b128 v[188:191], v139 offset:3072
	s_add_u32 s34, s34, 0x10000
	s_addc_u32 s35, s35, 0
	s_mov_b32 m0, s46
	ds_read_b128 v[198:201], v166 offset:32768
	ds_read_b128 v[202:205], v166 offset:33792
	ds_read_b128 v[206:209], v166 offset:34816
	ds_read_b128 v[210:213], v166 offset:35840
	ds_read_b128 v[214:217], v166 offset:36864
	ds_read_b128 v[218:221], v166 offset:37888
	ds_read_b128 v[222:225], v166 offset:38912
	ds_read_b128 v[226:229], v166 offset:39936
	global_load_lds_dwordx4 v136, s[34:35]
	s_mov_b32 m0, s47
	s_nop 0
	global_load_lds_dwordx4 v132, s[34:35]
	s_waitcnt vmcnt(8)
	s_waitcnt lgkmcnt(0)
	s_barrier
	s_setprio 1
	s_waitcnt lgkmcnt(0)
	v_mfma_f32_16x16x32_bf16 v[122:125], v[152:155], v[198:201], v[122:125]
	v_mfma_f32_16x16x32_bf16 v[114:117], v[168:171], v[198:201], v[114:117]
	v_mfma_f32_16x16x32_bf16 v[106:109], v[152:155], v[206:209], v[106:109]
	v_mfma_f32_16x16x32_bf16 v[98:101], v[168:171], v[206:209], v[98:101]
	v_mfma_f32_16x16x32_bf16 v[90:93], v[152:155], v[214:217], v[90:93]
	v_mfma_f32_16x16x32_bf16 v[82:85], v[168:171], v[214:217], v[82:85]
	v_mfma_f32_16x16x32_bf16 v[74:77], v[152:155], v[222:225], v[74:77]
	v_mfma_f32_16x16x32_bf16 v[66:69], v[168:171], v[222:225], v[66:69]
	v_mfma_f32_16x16x32_bf16 v[122:125], v[156:159], v[202:205], v[122:125]
	v_mfma_f32_16x16x32_bf16 v[114:117], v[172:175], v[202:205], v[114:117]
	v_mfma_f32_16x16x32_bf16 v[106:109], v[156:159], v[210:213], v[106:109]
	v_mfma_f32_16x16x32_bf16 v[98:101], v[172:175], v[210:213], v[98:101]
	v_mfma_f32_16x16x32_bf16 v[90:93], v[156:159], v[218:221], v[90:93]
	v_mfma_f32_16x16x32_bf16 v[82:85], v[172:175], v[218:221], v[82:85]
	v_mfma_f32_16x16x32_bf16 v[74:77], v[156:159], v[226:229], v[74:77]
	v_mfma_f32_16x16x32_bf16 v[66:69], v[172:175], v[226:229], v[66:69]
	s_setprio 0
	s_setprio 1
	v_mfma_f32_16x16x32_bf16 v[126:129], v[176:179], v[198:201], v[126:129]
	v_mfma_f32_16x16x32_bf16 v[118:121], v[184:187], v[198:201], v[118:121]
	v_mfma_f32_16x16x32_bf16 v[110:113], v[176:179], v[206:209], v[110:113]
	v_mfma_f32_16x16x32_bf16 v[102:105], v[184:187], v[206:209], v[102:105]
	v_mfma_f32_16x16x32_bf16 v[94:97], v[176:179], v[214:217], v[94:97]
	v_mfma_f32_16x16x32_bf16 v[86:89], v[184:187], v[214:217], v[86:89]
	v_mfma_f32_16x16x32_bf16 v[78:81], v[176:179], v[222:225], v[78:81]
	v_mfma_f32_16x16x32_bf16 v[70:73], v[184:187], v[222:225], v[70:73]
	v_mfma_f32_16x16x32_bf16 v[126:129], v[180:183], v[202:205], v[126:129]
	v_mfma_f32_16x16x32_bf16 v[118:121], v[188:191], v[202:205], v[118:121]
	v_mfma_f32_16x16x32_bf16 v[110:113], v[180:183], v[210:213], v[110:113]
	v_mfma_f32_16x16x32_bf16 v[102:105], v[188:191], v[210:213], v[102:105]
	v_mfma_f32_16x16x32_bf16 v[94:97], v[180:183], v[218:221], v[94:97]
	v_mfma_f32_16x16x32_bf16 v[86:89], v[188:191], v[218:221], v[86:89]
	v_mfma_f32_16x16x32_bf16 v[78:81], v[180:183], v[226:229], v[78:81]
	v_mfma_f32_16x16x32_bf16 v[70:73], v[188:191], v[226:229], v[70:73]
	s_setprio 0
	s_barrier
	s_add_u32 s98, s28, 0x80
	s_addc_u32 s99, s29, 0
	s_add_i32 s34, s59, s38
	s_mov_b32 m0, s34
	ds_read_b128 v[198:201], v166 offset:49152
	ds_read_b128 v[202:205], v166 offset:50176
	ds_read_b128 v[206:209], v166 offset:51200
	ds_read_b128 v[210:213], v166 offset:52224
	ds_read_b128 v[214:217], v166 offset:53248
	ds_read_b128 v[218:221], v166 offset:54272
	ds_read_b128 v[222:225], v166 offset:55296
	ds_read_b128 v[226:229], v166 offset:56320
	global_load_lds_dwordx4 v134, s[98:99]
	s_add_i32 m0, s34, 0x2000
	s_add_u32 s28, s28, 0x80080
	s_addc_u32 s29, s29, 0
	s_add_i32 s34, s60, s38
	global_load_lds_dwordx4 v130, s[98:99]
	s_mov_b32 m0, s34
	s_nop 0
	global_load_lds_dwordx4 v134, s[28:29]
	s_add_i32 m0, s34, 0x2000
	s_nop 0
	global_load_lds_dwordx4 v130, s[28:29]
	s_mov_b32 m0, s48
	s_nop 0
	global_load_lds_dwordx4 v136, s[100:101]
	s_mov_b32 m0, s49
	s_nop 0
	global_load_lds_dwordx4 v132, s[100:101]
	s_waitcnt vmcnt(8)
	s_waitcnt lgkmcnt(0)
	s_barrier
	s_setprio 1
	s_waitcnt lgkmcnt(0)
	v_mfma_f32_16x16x32_bf16 v[58:61], v[152:155], v[198:201], v[58:61]
	v_mfma_f32_16x16x32_bf16 v[50:53], v[168:171], v[198:201], v[50:53]
	v_mfma_f32_16x16x32_bf16 v[42:45], v[152:155], v[206:209], v[42:45]
	v_mfma_f32_16x16x32_bf16 v[34:37], v[168:171], v[206:209], v[34:37]
	v_mfma_f32_16x16x32_bf16 v[26:29], v[152:155], v[214:217], v[26:29]
	v_mfma_f32_16x16x32_bf16 v[18:21], v[168:171], v[214:217], v[18:21]
	v_mfma_f32_16x16x32_bf16 v[10:13], v[152:155], v[222:225], v[10:13]
	v_mfma_f32_16x16x32_bf16 v[6:9], v[168:171], v[222:225], v[6:9]
	v_mfma_f32_16x16x32_bf16 v[58:61], v[156:159], v[202:205], v[58:61]
	v_mfma_f32_16x16x32_bf16 v[50:53], v[172:175], v[202:205], v[50:53]
	v_mfma_f32_16x16x32_bf16 v[42:45], v[156:159], v[210:213], v[42:45]
	v_mfma_f32_16x16x32_bf16 v[34:37], v[172:175], v[210:213], v[34:37]
	v_mfma_f32_16x16x32_bf16 v[26:29], v[156:159], v[218:221], v[26:29]
	v_mfma_f32_16x16x32_bf16 v[18:21], v[172:175], v[218:221], v[18:21]
	v_mfma_f32_16x16x32_bf16 v[10:13], v[156:159], v[226:229], v[10:13]
	v_mfma_f32_16x16x32_bf16 v[6:9], v[172:175], v[226:229], v[6:9]
	s_setprio 0
	s_setprio 1
	v_mfma_f32_16x16x32_bf16 v[62:65], v[176:179], v[198:201], v[62:65]
	v_mfma_f32_16x16x32_bf16 v[54:57], v[184:187], v[198:201], v[54:57]
	v_mfma_f32_16x16x32_bf16 v[46:49], v[176:179], v[206:209], v[46:49]
	v_mfma_f32_16x16x32_bf16 v[38:41], v[184:187], v[206:209], v[38:41]
	v_mfma_f32_16x16x32_bf16 v[30:33], v[176:179], v[214:217], v[30:33]
	v_mfma_f32_16x16x32_bf16 v[22:25], v[184:187], v[214:217], v[22:25]
	v_mfma_f32_16x16x32_bf16 v[14:17], v[176:179], v[222:225], v[14:17]
	v_mfma_f32_16x16x32_bf16 v[2:5], v[184:187], v[222:225], v[2:5]
	v_mfma_f32_16x16x32_bf16 v[62:65], v[180:183], v[202:205], v[62:65]
	v_mfma_f32_16x16x32_bf16 v[54:57], v[188:191], v[202:205], v[54:57]
	v_mfma_f32_16x16x32_bf16 v[46:49], v[180:183], v[210:213], v[46:49]
	v_mfma_f32_16x16x32_bf16 v[38:41], v[188:191], v[210:213], v[38:41]
	v_mfma_f32_16x16x32_bf16 v[30:33], v[180:183], v[218:221], v[30:33]
	v_mfma_f32_16x16x32_bf16 v[22:25], v[188:191], v[218:221], v[22:25]
	v_mfma_f32_16x16x32_bf16 v[14:17], v[180:183], v[226:229], v[14:17]
	v_mfma_f32_16x16x32_bf16 v[2:5], v[188:191], v[226:229], v[2:5]
	s_setprio 0
	s_barrier
	s_add_i32 s57, s57, 2
	s_add_i32 s58, s58, 0x400000
	s_cmp_gt_u32 s57, 29
	s_mov_b64 s[28:29], s[30:31]

; #define PG8_STAGE(bufoff, gbase, voff) do { _Pragma("unroll") for (int _i = 0; _i < 2; ++_i) \
;         __builtin_amdgcn_global_load_lds((const unsigned*)((const char*)(gbase) + (voff)[_i]), (LAS unsigned*)(lds + (bufoff) + ldsw + _i * 8192), 16, 0, 0); } while (0)
; #define PG8_LDA(dst, b, h) do { _Pragma("unroll") for (int m = 0; m < 4; ++m) _Pragma("unroll") for (int k = 0; k < 2; ++k) dst[m][k] = *(const LAS bf16x8*)(lds + PG8_SA(b, h) + aoff + m * 2048 + k * 1024); } while (0)
; #define PG8_LDB(dst, b, h) do { _Pragma("unroll") for (int n = 0; n < 2; ++n) _Pragma("unroll") for (int k = 0; k < 2; ++k) dst[n][k] = *(const LAS bf16x8*)(lds + PG8_SB(b, h) + boff + n * 2048 + k * 1024); } while (0)
; #define PG8_WAIT_V(n) asm volatile("s_waitcnt vmcnt(" #n ")" ::: "memory")
; #define PG8_WAIT_L(n) asm volatile("s_waitcnt lgkmcnt(" #n ")" ::: "memory")
; #define PG8_BAR __builtin_amdgcn_s_barrier()
; template <class Epi, class Sched, int KC, bool ALIGN_EPI = false, bool SP2 = false, bool ATILED = false>
; __device__ __forceinline__ void gemm_phase(LAS unsigned char* lds, const Gemm g, const Sched& S, const Epi& E, int wave_s) {
;     ...
;         const bool has_next = S.next(ui + 1, nxt);
;         const char* nA = has_next ? (const char*)g.A + (size_t)nxt.pm * tstepA : cA; const char* nB = has_next ? (const char*)g.Bt + (size_t)nxt.pn * tstep : cB;
;         for (int t = 0; t < nt; t += 2) {
;             const bool last = (t == nt - 2);
;             const char* a1 = cA + PG8_AOFF(t + 1);
;             const char* a2 = last ? nA : cA + PG8_AOFF(t + 2); const char* b2 = last ? nB : cB + (size_t)(t + 2) * kstep;
;             const char* a3 = a2 + kstep; const char* b3 = b2 + kstep;
;             if (last && has_next) S.a_ready(nxt);
;             if constexpr (SP2) {
;             PG8_LDB(B0, 0, 0); PG8_LDB(B1, 0, 1); PG8_SCHED; PG8_LDA(At, 0, 0); PG8_STAGE(PG8_SA(1, 1), a1 + hstepA, voffA);
;             PG8_WAIT_V(8); PG8_WAIT_L(0); PG8_BAR; PG8_MMA(0, 0, At, B0); PG8_MMA(0, 1, At, B1); PG8_BAR; PG8_SCHED;
;     ...
; #pragma unroll
;         for (int a = 0; a < 2; ++a)
; #pragma unroll
;             for (int b = 0; b < 2; ++b)
; #pragma unroll
;                 for (int m = 0; m < 4; ++m)
; #pragma unroll
;                     for (int n = 0; n < 2; ++n) acc[a][b][m][n] = (f32x4){0.f, 0.f, 0.f, 0.f};
;         cur = nxt; cA = nA; cB = nB; ++ui;
.LBB0_317:
	s_add_u32 s50, s22, 0x100
	v_mov_b32_e32 v2, 0
	s_addc_u32 s51, s23, 0
	s_mov_b32 s52, -2
	v_mov_b32_e32 v3, v2
	v_mov_b32_e32 v4, v2
	v_mov_b32_e32 v5, v2
	v_mov_b32_e32 v6, v2
	v_mov_b32_e32 v7, v2
	v_mov_b32_e32 v8, v2
	v_mov_b32_e32 v9, v2
	v_mov_b32_e32 v18, v2
	v_mov_b32_e32 v19, v2
	v_mov_b32_e32 v20, v2
	v_mov_b32_e32 v21, v2
	v_mov_b32_e32 v22, v2
	v_mov_b32_e32 v23, v2
	v_mov_b32_e32 v24, v2
	v_mov_b32_e32 v25, v2
	v_mov_b32_e32 v34, v2
	v_mov_b32_e32 v35, v2
	v_mov_b32_e32 v36, v2
	v_mov_b32_e32 v37, v2
	v_mov_b32_e32 v38, v2
	v_mov_b32_e32 v39, v2
	v_mov_b32_e32 v40, v2
	v_mov_b32_e32 v41, v2
	v_mov_b32_e32 v50, v2
	v_mov_b32_e32 v51, v2
	v_mov_b32_e32 v52, v2
	v_mov_b32_e32 v53, v2
	v_mov_b32_e32 v54, v2
	v_mov_b32_e32 v55, v2
	v_mov_b32_e32 v56, v2
	v_mov_b32_e32 v57, v2
	v_mov_b32_e32 v10, v2
	v_mov_b32_e32 v11, v2
	v_mov_b32_e32 v12, v2
	v_mov_b32_e32 v13, v2
	v_mov_b32_e32 v14, v2
	v_mov_b32_e32 v15, v2
	v_mov_b32_e32 v16, v2
	v_mov_b32_e32 v17, v2
	v_mov_b32_e32 v26, v2
	v_mov_b32_e32 v27, v2
	v_mov_b32_e32 v28, v2
	v_mov_b32_e32 v29, v2
	v_mov_b32_e32 v30, v2
	v_mov_b32_e32 v31, v2
	v_mov_b32_e32 v32, v2
	v_mov_b32_e32 v33, v2
	v_mov_b32_e32 v42, v2
	v_mov_b32_e32 v43, v2
	v_mov_b32_e32 v44, v2
	v_mov_b32_e32 v45, v2
	v_mov_b32_e32 v46, v2
	v_mov_b32_e32 v47, v2
	v_mov_b32_e32 v48, v2
	v_mov_b32_e32 v49, v2
	v_mov_b32_e32 v58, v2
	v_mov_b32_e32 v59, v2
	v_mov_b32_e32 v60, v2
	v_mov_b32_e32 v61, v2
	v_mov_b32_e32 v62, v2
	v_mov_b32_e32 v63, v2
	v_mov_b32_e32 v64, v2
	v_mov_b32_e32 v65, v2
	v_mov_b32_e32 v66, v2
	v_mov_b32_e32 v67, v2
	v_mov_b32_e32 v68, v2
	v_mov_b32_e32 v69, v2
	v_mov_b32_e32 v70, v2
	v_mov_b32_e32 v71, v2
	v_mov_b32_e32 v72, v2
	v_mov_b32_e32 v73, v2
	v_mov_b32_e32 v86, v2
	v_mov_b32_e32 v87, v2
	v_mov_b32_e32 v88, v2
	v_mov_b32_e32 v89, v2
	v_mov_b32_e32 v90, v2
	v_mov_b32_e32 v91, v2
	v_mov_b32_e32 v92, v2
	v_mov_b32_e32 v93, v2
	v_mov_b32_e32 v110, v2
	v_mov_b32_e32 v111, v2
	v_mov_b32_e32 v112, v2
	v_mov_b32_e32 v113, v2
	v_mov_b32_e32 v118, v2
	v_mov_b32_e32 v119, v2
	v_mov_b32_e32 v120, v2
	v_mov_b32_e32 v121, v2
	v_mov_b32_e32 v138, v2
	v_mov_b32_e32 v139, v2
	v_mov_b32_e32 v140, v2
	v_mov_b32_e32 v141, v2
	v_mov_b32_e32 v142, v2
	v_mov_b32_e32 v143, v2
	v_mov_b32_e32 v144, v2
	v_mov_b32_e32 v145, v2
	v_mov_b32_e32 v74, v2
	v_mov_b32_e32 v75, v2
	v_mov_b32_e32 v76, v2
	v_mov_b32_e32 v77, v2
	v_mov_b32_e32 v78, v2
	v_mov_b32_e32 v79, v2
	v_mov_b32_e32 v80, v2
	v_mov_b32_e32 v81, v2
	v_mov_b32_e32 v98, v2
	v_mov_b32_e32 v99, v2
	v_mov_b32_e32 v100, v2
	v_mov_b32_e32 v101, v2
	v_mov_b32_e32 v102, v2
	v_mov_b32_e32 v103, v2
	v_mov_b32_e32 v104, v2
	v_mov_b32_e32 v105, v2
	v_mov_b32_e32 v122, v2
	v_mov_b32_e32 v123, v2
	v_mov_b32_e32 v124, v2
	v_mov_b32_e32 v125, v2
	v_mov_b32_e32 v126, v2
	v_mov_b32_e32 v127, v2
	v_mov_b32_e32 v128, v2
	v_mov_b32_e32 v129, v2
	v_mov_b32_e32 v158, v2
	v_mov_b32_e32 v159, v2
	v_mov_b32_e32 v160, v2
	v_mov_b32_e32 v161, v2
	v_mov_b32_e32 v162, v2
	v_mov_b32_e32 v163, v2
	v_mov_b32_e32 v164, v2
	v_mov_b32_e32 v165, v2
	s_add_u32 s8, s20, 0x100
	s_addc_u32 s9, s21, 0
	s_add_i32 s53, 0, 0x10000
	s_cmpk_eq_i32 s52, 0x54
	s_cselect_b32 s25, s17, s9
	s_cselect_b32 s24, s16, s8
	s_cselect_b32 s23, s11, s51
	s_cselect_b32 s22, s10, s50
	s_add_i32 s54, 0, 0x14000
	v_add_u32_e32 v114, s53, v249
	v_add_u32_e32 v150, s54, v249
	ds_read_b128 v[82:85], v114
	ds_read_b128 v[94:97], v114 offset:1024
	ds_read_b128 v[106:109], v114 offset:2048
	ds_read_b128 v[114:117], v114 offset:3072
	ds_read_b128 v[130:133], v150
	ds_read_b128 v[134:137], v150 offset:1024
	ds_read_b128 v[146:149], v150 offset:2048
	ds_read_b128 v[150:153], v150 offset:3072
	s_add_i32 m0, s36, 0xc000
	ds_read_b128 v[154:157], v251
	ds_read_b128 v[166:169], v251 offset:1024
	ds_read_b128 v[170:173], v251 offset:2048
	ds_read_b128 v[174:177], v251 offset:3072
	ds_read_b128 v[178:181], v251 offset:4096
	ds_read_b128 v[182:185], v251 offset:5120
	ds_read_b128 v[186:189], v251 offset:6144
	ds_read_b128 v[194:197], v251 offset:7168
	global_load_lds_dwordx4 v204, s[20:21]
	s_add_i32 m0, s36, 0xe000
	s_nop 0
	global_load_lds_dwordx4 v202, s[20:21]
	s_waitcnt vmcnt(32)
	s_waitcnt lgkmcnt(0)
	s_barrier
	s_setprio 1
	s_waitcnt lgkmcnt(0)
	v_mfma_f32_16x16x32_bf16 v[162:165], v[82:85], v[154:157], v[162:165]
	v_mfma_f32_16x16x32_bf16 v[158:161], v[106:109], v[154:157], v[158:161]
	v_mfma_f32_16x16x32_bf16 v[126:129], v[82:85], v[170:173], v[126:129]
	v_mfma_f32_16x16x32_bf16 v[122:125], v[106:109], v[170:173], v[122:125]
	v_mfma_f32_16x16x32_bf16 v[102:105], v[82:85], v[178:181], v[102:105]
	v_mfma_f32_16x16x32_bf16 v[98:101], v[106:109], v[178:181], v[98:101]
	v_mfma_f32_16x16x32_bf16 v[78:81], v[82:85], v[186:189], v[78:81]
	v_mfma_f32_16x16x32_bf16 v[74:77], v[106:109], v[186:189], v[74:77]
	v_mfma_f32_16x16x32_bf16 v[162:165], v[94:97], v[166:169], v[162:165]
	v_mfma_f32_16x16x32_bf16 v[158:161], v[114:117], v[166:169], v[158:161]
	v_mfma_f32_16x16x32_bf16 v[126:129], v[94:97], v[174:177], v[126:129]
	v_mfma_f32_16x16x32_bf16 v[122:125], v[114:117], v[174:177], v[122:125]
	v_mfma_f32_16x16x32_bf16 v[102:105], v[94:97], v[182:185], v[102:105]
	v_mfma_f32_16x16x32_bf16 v[98:101], v[114:117], v[182:185], v[98:101]
	v_mfma_f32_16x16x32_bf16 v[78:81], v[94:97], v[194:197], v[78:81]
	v_mfma_f32_16x16x32_bf16 v[74:77], v[114:117], v[194:197], v[74:77]
	s_setprio 0
	s_setprio 1
	v_mfma_f32_16x16x32_bf16 v[142:145], v[130:133], v[154:157], v[142:145]
	v_mfma_f32_16x16x32_bf16 v[138:141], v[146:149], v[154:157], v[138:141]
	v_mfma_f32_16x16x32_bf16 v[118:121], v[130:133], v[170:173], v[118:121]
	v_mfma_f32_16x16x32_bf16 v[110:113], v[146:149], v[170:173], v[110:113]
	v_mfma_f32_16x16x32_bf16 v[90:93], v[130:133], v[178:181], v[90:93]
	v_mfma_f32_16x16x32_bf16 v[86:89], v[146:149], v[178:181], v[86:89]
	v_mfma_f32_16x16x32_bf16 v[70:73], v[130:133], v[186:189], v[70:73]
	v_mfma_f32_16x16x32_bf16 v[66:69], v[146:149], v[186:189], v[66:69]
	v_mfma_f32_16x16x32_bf16 v[142:145], v[134:137], v[166:169], v[142:145]
	v_mfma_f32_16x16x32_bf16 v[138:141], v[150:153], v[166:169], v[138:141]
	v_mfma_f32_16x16x32_bf16 v[118:121], v[134:137], v[174:177], v[118:121]
	v_mfma_f32_16x16x32_bf16 v[110:113], v[150:153], v[174:177], v[110:113]
	v_mfma_f32_16x16x32_bf16 v[90:93], v[134:137], v[182:185], v[90:93]
	v_mfma_f32_16x16x32_bf16 v[86:89], v[150:153], v[182:185], v[86:89]
	v_mfma_f32_16x16x32_bf16 v[70:73], v[134:137], v[194:197], v[70:73]
	v_mfma_f32_16x16x32_bf16 v[66:69], v[150:153], v[194:197], v[66:69]
	s_setprio 0
	s_barrier
; #define PG8_STAGE(bufoff, gbase, voff) do { _Pragma("unroll") for (int _i = 0; _i < 2; ++_i) \
;         __builtin_amdgcn_global_load_lds((const unsigned*)((const char*)(gbase) + (voff)[_i]), (LAS unsigned*)(lds + (bufoff) + ldsw + _i * 8192), 16, 0, 0); } while (0)
; #define PG8_LDA(dst, b, h) do { _Pragma("unroll") for (int m = 0; m < 4; ++m) _Pragma("unroll") for (int k = 0; k < 2; ++k) dst[m][k] = *(const LAS bf16x8*)(lds + PG8_SA(b, h) + aoff + m * 2048 + k * 1024); } while (0)
; #define PG8_LDB(dst, b, h) do { _Pragma("unroll") for (int n = 0; n < 2; ++n) _Pragma("unroll") for (int k = 0; k < 2; ++k) dst[n][k] = *(const LAS bf16x8*)(lds + PG8_SB(b, h) + boff + n * 2048 + k * 1024); } while (0)
; #define PG8_MMA(ai, bj, At, Bt) do { __builtin_amdgcn_s_setprio(1); _Pragma("unroll") for (int m = 0; m < 4; ++m) _Pragma("unroll") for (int n = 0; n < 2; ++n) _Pragma("unroll") for (int k = 0; k < 2; ++k) \
;         acc[ai][bj][m][n] = __builtin_amdgcn_mfma_f32_16x16x32_bf16(Bt[n][k], At[m][k], acc[ai][bj][m][n], 0, 0, 0); __builtin_amdgcn_s_setprio(0); } while (0)
; #define PG8_WAIT_V(n) asm volatile("s_waitcnt vmcnt(" #n ")" ::: "memory")
; #define PG8_WAIT_L(n) asm volatile("s_waitcnt lgkmcnt(" #n ")" ::: "memory")
; #define PG8_BAR __builtin_amdgcn_s_barrier()
; #define PG8_SCHED __builtin_amdgcn_sched_barrier(0)
; template <class Epi, class Sched, int KC, bool ALIGN_EPI = false, bool SP2 = false, bool ATILED = false>
; __device__ __forceinline__ void gemm_phase(LAS unsigned char* lds, const Gemm g, const Sched& S, const Epi& E, int wave_s) {
;     ...
;             PG8_LDA(At, 0, 1); PG8_STAGE(PG8_SB(0, 0), b2, voffB); PG8_STAGE(PG8_SB(0, 1), b2 + hstepB, voffB); PG8_STAGE(PG8_SA(0, 0), a2, voffA);
;             PG8_WAIT_V(8); PG8_WAIT_L(0); PG8_BAR; PG8_MMA(1, 0, At, B0); PG8_MMA(1, 1, At, B1); PG8_BAR; PG8_SCHED;
;             PG8_LDB(B0, 1, 0); PG8_LDB(B1, 1, 1); PG8_SCHED; PG8_LDA(At, 1, 0); PG8_STAGE(PG8_SA(0, 1), a2 + hstepA, voffA);
;             PG8_WAIT_V(8); PG8_WAIT_L(0); PG8_BAR; PG8_MMA(0, 0, At, B0); PG8_MMA(0, 1, At, B1); PG8_BAR; PG8_SCHED;
	s_add_i32 s20, s53, s35
	s_mov_b32 m0, s20
	ds_read_b128 v[154:157], v251 offset:16384
	ds_read_b128 v[166:169], v251 offset:17408
	ds_read_b128 v[170:173], v251 offset:18432
	ds_read_b128 v[174:177], v251 offset:19456
	ds_read_b128 v[178:181], v251 offset:20480
	ds_read_b128 v[182:185], v251 offset:21504
	ds_read_b128 v[186:189], v251 offset:22528
	ds_read_b128 v[194:197], v251 offset:23552
	global_load_lds_dwordx4 v0, s[22:23]
	s_add_i32 m0, s20, 0x2000
	s_add_u32 s20, s22, 0x58000
	s_addc_u32 s21, s23, 0
	s_add_i32 s53, s54, s35
	global_load_lds_dwordx4 v198, s[22:23]
	s_mov_b32 m0, s53
	s_nop 0
	global_load_lds_dwordx4 v0, s[20:21]
	s_add_i32 m0, s53, 0x2000
	s_nop 0
	global_load_lds_dwordx4 v198, s[20:21]
	s_mov_b32 m0, s36
	s_nop 0
	global_load_lds_dwordx4 v190, s[24:25]
	s_mov_b32 m0, s37
	s_nop 0
	global_load_lds_dwordx4 v192, s[24:25]
	s_waitcnt vmcnt(32)
	s_waitcnt lgkmcnt(0)
	s_barrier
	s_setprio 1
	s_waitcnt lgkmcnt(0)
	v_mfma_f32_16x16x32_bf16 v[62:65], v[82:85], v[154:157], v[62:65]
	v_mfma_f32_16x16x32_bf16 v[58:61], v[106:109], v[154:157], v[58:61]
	v_mfma_f32_16x16x32_bf16 v[46:49], v[82:85], v[170:173], v[46:49]
	v_mfma_f32_16x16x32_bf16 v[42:45], v[106:109], v[170:173], v[42:45]
	v_mfma_f32_16x16x32_bf16 v[30:33], v[82:85], v[178:181], v[30:33]
	v_mfma_f32_16x16x32_bf16 v[26:29], v[106:109], v[178:181], v[26:29]
	v_mfma_f32_16x16x32_bf16 v[14:17], v[82:85], v[186:189], v[14:17]
	v_mfma_f32_16x16x32_bf16 v[10:13], v[106:109], v[186:189], v[10:13]
	v_mfma_f32_16x16x32_bf16 v[62:65], v[94:97], v[166:169], v[62:65]
	v_mfma_f32_16x16x32_bf16 v[58:61], v[114:117], v[166:169], v[58:61]
	v_mfma_f32_16x16x32_bf16 v[46:49], v[94:97], v[174:177], v[46:49]
	v_mfma_f32_16x16x32_bf16 v[42:45], v[114:117], v[174:177], v[42:45]
	v_mfma_f32_16x16x32_bf16 v[30:33], v[94:97], v[182:185], v[30:33]
	v_mfma_f32_16x16x32_bf16 v[26:29], v[114:117], v[182:185], v[26:29]
	v_mfma_f32_16x16x32_bf16 v[14:17], v[94:97], v[194:197], v[14:17]
	v_mfma_f32_16x16x32_bf16 v[10:13], v[114:117], v[194:197], v[10:13]
	s_setprio 0
	s_setprio 1
	v_mfma_f32_16x16x32_bf16 v[54:57], v[130:133], v[154:157], v[54:57]
	v_mfma_f32_16x16x32_bf16 v[50:53], v[146:149], v[154:157], v[50:53]
	v_mfma_f32_16x16x32_bf16 v[38:41], v[130:133], v[170:173], v[38:41]
	v_mfma_f32_16x16x32_bf16 v[34:37], v[146:149], v[170:173], v[34:37]
	v_mfma_f32_16x16x32_bf16 v[22:25], v[130:133], v[178:181], v[22:25]
	v_mfma_f32_16x16x32_bf16 v[18:21], v[146:149], v[178:181], v[18:21]
	v_mfma_f32_16x16x32_bf16 v[6:9], v[130:133], v[186:189], v[6:9]
	v_mfma_f32_16x16x32_bf16 v[2:5], v[146:149], v[186:189], v[2:5]
	v_mfma_f32_16x16x32_bf16 v[54:57], v[134:137], v[166:169], v[54:57]
	v_mfma_f32_16x16x32_bf16 v[50:53], v[150:153], v[166:169], v[50:53]
	v_mfma_f32_16x16x32_bf16 v[38:41], v[134:137], v[174:177], v[38:41]
	v_mfma_f32_16x16x32_bf16 v[34:37], v[150:153], v[174:177], v[34:37]
	v_mfma_f32_16x16x32_bf16 v[22:25], v[134:137], v[182:185], v[22:25]
	v_mfma_f32_16x16x32_bf16 v[18:21], v[150:153], v[182:185], v[18:21]
	v_mfma_f32_16x16x32_bf16 v[6:9], v[134:137], v[194:197], v[6:9]
	v_mfma_f32_16x16x32_bf16 v[2:5], v[150:153], v[194:197], v[2:5]
	s_setprio 0
	s_barrier
	s_add_i32 s53, 0, 0x18000
	s_add_i32 s54, 0, 0x1c000
	v_add_u32_e32 v114, s53, v249
	v_add_u32_e32 v150, s54, v249
	ds_read_b128 v[82:85], v114
	ds_read_b128 v[94:97], v114 offset:1024
	ds_read_b128 v[106:109], v114 offset:2048
	ds_read_b128 v[114:117], v114 offset:3072
	ds_read_b128 v[130:133], v150
	ds_read_b128 v[134:137], v150 offset:1024
	ds_read_b128 v[146:149], v150 offset:2048
	ds_read_b128 v[150:153], v150 offset:3072
	s_add_u32 s20, s24, 0x160000
	s_addc_u32 s21, s25, 0
	s_mov_b32 m0, s38
	ds_read_b128 v[154:157], v251 offset:32768
	ds_read_b128 v[166:169], v251 offset:33792
	ds_read_b128 v[170:173], v251 offset:34816
	ds_read_b128 v[174:177], v251 offset:35840
	ds_read_b128 v[178:181], v251 offset:36864
	ds_read_b128 v[182:185], v251 offset:37888
	ds_read_b128 v[186:189], v251 offset:38912
	ds_read_b128 v[194:197], v251 offset:39936
	global_load_lds_dwordx4 v190, s[20:21]
	s_mov_b32 m0, s39
	s_nop 0
	global_load_lds_dwordx4 v192, s[20:21]
	s_waitcnt vmcnt(8)
	s_waitcnt lgkmcnt(0)
	s_barrier
; #define PG8_STAGE(bufoff, gbase, voff) do { _Pragma("unroll") for (int _i = 0; _i < 2; ++_i) \
;         __builtin_amdgcn_global_load_lds((const unsigned*)((const char*)(gbase) + (voff)[_i]), (LAS unsigned*)(lds + (bufoff) + ldsw + _i * 8192), 16, 0, 0); } while (0)
; #define PG8_LDA(dst, b, h) do { _Pragma("unroll") for (int m = 0; m < 4; ++m) _Pragma("unroll") for (int k = 0; k < 2; ++k) dst[m][k] = *(const LAS bf16x8*)(lds + PG8_SA(b, h) + aoff + m * 2048 + k * 1024); } while (0)
; #define PG8_LDB(dst, b, h) do { _Pragma("unroll") for (int n = 0; n < 2; ++n) _Pragma("unroll") for (int k = 0; k < 2; ++k) dst[n][k] = *(const LAS bf16x8*)(lds + PG8_SB(b, h) + boff + n * 2048 + k * 1024); } while (0)
; #define PG8_MMA(ai, bj, At, Bt) do { __builtin_amdgcn_s_setprio(1); _Pragma("unroll") for (int m = 0; m < 4; ++m) _Pragma("unroll") for (int n = 0; n < 2; ++n) _Pragma("unroll") for (int k = 0; k < 2; ++k) \
;         acc[ai][bj][m][n] = __builtin_amdgcn_mfma_f32_16x16x32_bf16(Bt[n][k], At[m][k], acc[ai][bj][m][n], 0, 0, 0); __builtin_amdgcn_s_setprio(0); } while (0)
; #define PG8_WAIT_V(n) asm volatile("s_waitcnt vmcnt(" #n ")" ::: "memory")
; #define PG8_WAIT_L(n) asm volatile("s_waitcnt lgkmcnt(" #n ")" ::: "memory")
; #define PG8_BAR __builtin_amdgcn_s_barrier()
; #define PG8_SCHED __builtin_amdgcn_sched_barrier(0)
; template <class Epi, class Sched, int KC, bool ALIGN_EPI = false, bool SP2 = false, bool ATILED = false>
; __device__ __forceinline__ void gemm_phase(LAS unsigned char* lds, const Gemm g, const Sched& S, const Epi& E, int wave_s) {
;     ...
;             PG8_LDB(B0, 1, 0); PG8_LDB(B1, 1, 1); PG8_SCHED; PG8_LDA(At, 1, 0); PG8_STAGE(PG8_SA(0, 1), a2 + hstepA, voffA);
;             PG8_WAIT_V(8); PG8_WAIT_L(0); PG8_BAR; PG8_MMA(0, 0, At, B0); PG8_MMA(0, 1, At, B1); PG8_BAR; PG8_SCHED;
;             PG8_LDA(At, 1, 1); PG8_STAGE(PG8_SB(1, 0), b3, voffB); PG8_STAGE(PG8_SB(1, 1), b3 + hstepB, voffB); PG8_STAGE(PG8_SA(1, 0), a3, voffA);
;             PG8_WAIT_V(8); PG8_WAIT_L(0); PG8_BAR; PG8_MMA(1, 0, At, B0); PG8_MMA(1, 1, At, B1); PG8_BAR; PG8_SCHED;
	s_setprio 1
	s_waitcnt lgkmcnt(0)
	v_mfma_f32_16x16x32_bf16 v[162:165], v[82:85], v[154:157], v[162:165]
	v_mfma_f32_16x16x32_bf16 v[158:161], v[106:109], v[154:157], v[158:161]
	v_mfma_f32_16x16x32_bf16 v[126:129], v[82:85], v[170:173], v[126:129]
	v_mfma_f32_16x16x32_bf16 v[122:125], v[106:109], v[170:173], v[122:125]
	v_mfma_f32_16x16x32_bf16 v[102:105], v[82:85], v[178:181], v[102:105]
	v_mfma_f32_16x16x32_bf16 v[98:101], v[106:109], v[178:181], v[98:101]
	v_mfma_f32_16x16x32_bf16 v[78:81], v[82:85], v[186:189], v[78:81]
	v_mfma_f32_16x16x32_bf16 v[74:77], v[106:109], v[186:189], v[74:77]
	v_mfma_f32_16x16x32_bf16 v[162:165], v[94:97], v[166:169], v[162:165]
	v_mfma_f32_16x16x32_bf16 v[158:161], v[114:117], v[166:169], v[158:161]
	v_mfma_f32_16x16x32_bf16 v[126:129], v[94:97], v[174:177], v[126:129]
	v_mfma_f32_16x16x32_bf16 v[122:125], v[114:117], v[174:177], v[122:125]
	v_mfma_f32_16x16x32_bf16 v[102:105], v[94:97], v[182:185], v[102:105]
	v_mfma_f32_16x16x32_bf16 v[98:101], v[114:117], v[182:185], v[98:101]
	v_mfma_f32_16x16x32_bf16 v[78:81], v[94:97], v[194:197], v[78:81]
	v_mfma_f32_16x16x32_bf16 v[74:77], v[114:117], v[194:197], v[74:77]
	s_setprio 0
	s_setprio 1
	v_mfma_f32_16x16x32_bf16 v[142:145], v[130:133], v[154:157], v[142:145]
	v_mfma_f32_16x16x32_bf16 v[138:141], v[146:149], v[154:157], v[138:141]
	v_mfma_f32_16x16x32_bf16 v[118:121], v[130:133], v[170:173], v[118:121]
	v_mfma_f32_16x16x32_bf16 v[110:113], v[146:149], v[170:173], v[110:113]
	v_mfma_f32_16x16x32_bf16 v[90:93], v[130:133], v[178:181], v[90:93]
	v_mfma_f32_16x16x32_bf16 v[86:89], v[146:149], v[178:181], v[86:89]
	v_mfma_f32_16x16x32_bf16 v[70:73], v[130:133], v[186:189], v[70:73]
	v_mfma_f32_16x16x32_bf16 v[66:69], v[146:149], v[186:189], v[66:69]
	v_mfma_f32_16x16x32_bf16 v[142:145], v[134:137], v[166:169], v[142:145]
	v_mfma_f32_16x16x32_bf16 v[138:141], v[150:153], v[166:169], v[138:141]
	v_mfma_f32_16x16x32_bf16 v[118:121], v[134:137], v[174:177], v[118:121]
	v_mfma_f32_16x16x32_bf16 v[110:113], v[150:153], v[174:177], v[110:113]
	v_mfma_f32_16x16x32_bf16 v[90:93], v[134:137], v[182:185], v[90:93]
	v_mfma_f32_16x16x32_bf16 v[86:89], v[150:153], v[182:185], v[86:89]
	v_mfma_f32_16x16x32_bf16 v[70:73], v[134:137], v[194:197], v[70:73]
	v_mfma_f32_16x16x32_bf16 v[66:69], v[150:153], v[194:197], v[66:69]
	s_setprio 0
	s_barrier
	s_add_u32 s98, s22, 0x80
	s_addc_u32 s99, s23, 0
	s_add_u32 s100, s24, 0x80
	s_addc_u32 s101, s25, 0
	s_add_i32 s20, s53, s35
	s_mov_b32 m0, s20
	ds_read_b128 v[154:157], v251 offset:49152
	ds_read_b128 v[166:169], v251 offset:50176
	ds_read_b128 v[170:173], v251 offset:51200
	ds_read_b128 v[174:177], v251 offset:52224
	ds_read_b128 v[178:181], v251 offset:53248
	ds_read_b128 v[182:185], v251 offset:54272
	ds_read_b128 v[186:189], v251 offset:55296
	ds_read_b128 v[194:197], v251 offset:56320
	global_load_lds_dwordx4 v0, s[98:99]
	s_add_i32 m0, s20, 0x2000
	s_add_u32 s20, s22, 0x58080
	s_addc_u32 s21, s23, 0
	s_add_i32 s22, s54, s35
	global_load_lds_dwordx4 v198, s[98:99]
	s_mov_b32 m0, s22
	s_nop 0
	global_load_lds_dwordx4 v0, s[20:21]
	s_add_i32 m0, s22, 0x2000
	s_nop 0
	global_load_lds_dwordx4 v198, s[20:21]
	s_mov_b32 m0, s43
	s_nop 0
	global_load_lds_dwordx4 v190, s[100:101]
	s_mov_b32 m0, s44
	s_nop 0
	global_load_lds_dwordx4 v192, s[100:101]
	s_waitcnt vmcnt(8)
	s_waitcnt lgkmcnt(0)
	s_barrier
	s_setprio 1
	s_waitcnt lgkmcnt(0)
	v_mfma_f32_16x16x32_bf16 v[62:65], v[82:85], v[154:157], v[62:65]
	v_mfma_f32_16x16x32_bf16 v[58:61], v[106:109], v[154:157], v[58:61]
	v_mfma_f32_16x16x32_bf16 v[46:49], v[82:85], v[170:173], v[46:49]
	v_mfma_f32_16x16x32_bf16 v[42:45], v[106:109], v[170:173], v[42:45]
	v_mfma_f32_16x16x32_bf16 v[30:33], v[82:85], v[178:181], v[30:33]
	v_mfma_f32_16x16x32_bf16 v[26:29], v[106:109], v[178:181], v[26:29]
	v_mfma_f32_16x16x32_bf16 v[14:17], v[82:85], v[186:189], v[14:17]
	v_mfma_f32_16x16x32_bf16 v[10:13], v[106:109], v[186:189], v[10:13]
	v_mfma_f32_16x16x32_bf16 v[62:65], v[94:97], v[166:169], v[62:65]
	v_mfma_f32_16x16x32_bf16 v[58:61], v[114:117], v[166:169], v[58:61]
	v_mfma_f32_16x16x32_bf16 v[46:49], v[94:97], v[174:177], v[46:49]
	v_mfma_f32_16x16x32_bf16 v[42:45], v[114:117], v[174:177], v[42:45]
	v_mfma_f32_16x16x32_bf16 v[30:33], v[94:97], v[182:185], v[30:33]
	v_mfma_f32_16x16x32_bf16 v[26:29], v[114:117], v[182:185], v[26:29]
	v_mfma_f32_16x16x32_bf16 v[14:17], v[94:97], v[194:197], v[14:17]
	v_mfma_f32_16x16x32_bf16 v[10:13], v[114:117], v[194:197], v[10:13]
	s_setprio 0
	s_setprio 1
	v_mfma_f32_16x16x32_bf16 v[54:57], v[130:133], v[154:157], v[54:57]
	v_mfma_f32_16x16x32_bf16 v[50:53], v[146:149], v[154:157], v[50:53]
	v_mfma_f32_16x16x32_bf16 v[38:41], v[130:133], v[170:173], v[38:41]
	v_mfma_f32_16x16x32_bf16 v[34:37], v[146:149], v[170:173], v[34:37]
	v_mfma_f32_16x16x32_bf16 v[22:25], v[130:133], v[178:181], v[22:25]
	v_mfma_f32_16x16x32_bf16 v[18:21], v[146:149], v[178:181], v[18:21]
	v_mfma_f32_16x16x32_bf16 v[6:9], v[130:133], v[186:189], v[6:9]
	v_mfma_f32_16x16x32_bf16 v[2:5], v[146:149], v[186:189], v[2:5]
	v_mfma_f32_16x16x32_bf16 v[54:57], v[134:137], v[166:169], v[54:57]
	v_mfma_f32_16x16x32_bf16 v[50:53], v[150:153], v[166:169], v[50:53]
	v_mfma_f32_16x16x32_bf16 v[38:41], v[134:137], v[174:177], v[38:41]
	v_mfma_f32_16x16x32_bf16 v[34:37], v[150:153], v[174:177], v[34:37]
	v_mfma_f32_16x16x32_bf16 v[22:25], v[134:137], v[182:185], v[22:25]
	v_mfma_f32_16x16x32_bf16 v[18:21], v[150:153], v[182:185], v[18:21]
	v_mfma_f32_16x16x32_bf16 v[6:9], v[134:137], v[194:197], v[6:9]
	v_mfma_f32_16x16x32_bf16 v[2:5], v[150:153], v[194:197], v[2:5]
	s_setprio 0
	s_barrier
	s_add_i32 s52, s52, 2
	s_add_u32 s50, s50, 0x100
	s_addc_u32 s51, s51, 0
	s_cmpk_gt_u32 s52, 0x55
	s_mov_b64 s[20:21], s[8:9]

; #define PG8_STAGE(bufoff, gbase, voff) do { _Pragma("unroll") for (int _i = 0; _i < 2; ++_i) \
;         __builtin_amdgcn_global_load_lds((const unsigned*)((const char*)(gbase) + (voff)[_i]), (LAS unsigned*)(lds + (bufoff) + ldsw + _i * 8192), 16, 0, 0); } while (0)
; #define PG8_LDA(dst, b, h) do { _Pragma("unroll") for (int m = 0; m < 4; ++m) _Pragma("unroll") for (int k = 0; k < 2; ++k) dst[m][k] = *(const LAS bf16x8*)(lds + PG8_SA(b, h) + aoff + m * 2048 + k * 1024); } while (0)
; #define PG8_LDB(dst, b, h) do { _Pragma("unroll") for (int n = 0; n < 2; ++n) _Pragma("unroll") for (int k = 0; k < 2; ++k) dst[n][k] = *(const LAS bf16x8*)(lds + PG8_SB(b, h) + boff + n * 2048 + k * 1024); } while (0)
; #define PG8_WAIT_V(n) asm volatile("s_waitcnt vmcnt(" #n ")" ::: "memory")
; #define PG8_WAIT_L(n) asm volatile("s_waitcnt lgkmcnt(" #n ")" ::: "memory")
; #define PG8_BAR __builtin_amdgcn_s_barrier()
; template <class Epi, class Sched, int KC, bool ALIGN_EPI = false, bool SP2 = false, bool ATILED = false>
; __device__ __forceinline__ void gemm_phase(LAS unsigned char* lds, const Gemm g, const Sched& S, const Epi& E, int wave_s) {
;     ...
;         const bool has_next = S.next(ui + 1, nxt);
;         const char* nA = has_next ? (const char*)g.A + (size_t)nxt.pm * tstepA : cA; const char* nB = has_next ? (const char*)g.Bt + (size_t)nxt.pn * tstep : cB;
;         for (int t = 0; t < nt; t += 2) {
;             const bool last = (t == nt - 2);
;             const char* a1 = cA + PG8_AOFF(t + 1);
;             const char* a2 = last ? nA : cA + PG8_AOFF(t + 2); const char* b2 = last ? nB : cB + (size_t)(t + 2) * kstep;
;             const char* a3 = a2 + kstep; const char* b3 = b2 + kstep;
;             if (last && has_next) S.a_ready(nxt);
;             if constexpr (SP2) {
;             PG8_LDB(B0, 0, 0); PG8_LDB(B1, 0, 1); PG8_SCHED; PG8_LDA(At, 0, 0); PG8_STAGE(PG8_SA(1, 1), a1 + hstepA, voffA);
;             PG8_WAIT_V(8); PG8_WAIT_L(0); PG8_BAR; PG8_MMA(0, 0, At, B0); PG8_MMA(0, 1, At, B1); PG8_BAR; PG8_SCHED;
;     ...
; #pragma unroll
;         for (int a = 0; a < 2; ++a)
; #pragma unroll
;             for (int b = 0; b < 2; ++b)
; #pragma unroll
;                 for (int m = 0; m < 4; ++m)
; #pragma unroll
;                     for (int n = 0; n < 2; ++n) acc[a][b][m][n] = (f32x4){0.f, 0.f, 0.f, 0.f};
;         cur = nxt; cA = nA; cB = nB; ++ui;
.LBB0_429:
	s_ashr_i32 s19, s18, 31
	s_lshl_b64 s[20:21], s[18:19], 17
	s_add_u32 s20, s42, s20
	s_addc_u32 s21, s43, s21
	s_and_b64 s[22:23], s[6:7], exec
	s_cselect_b32 s19, s21, s27
	s_cselect_b32 s61, s20, s26
	s_ashr_i32 s17, s16, 31
	s_lshl_b64 s[22:23], s[16:17], 20
	s_add_u32 s22, s44, s22
	s_addc_u32 s23, s45, s23
	s_and_b64 s[30:31], s[6:7], exec
	s_cselect_b32 s17, s23, s29
	s_cselect_b32 s62, s22, s28
	s_add_u32 s63, s28, 0x100
	v_mov_b32_e32 v2, 0
	s_addc_u32 s64, s29, 0
	s_mov_b32 s65, -2
	s_mov_b64 s[28:29], 0
	s_mov_b32 s66, 0x400000
	v_mov_b32_e32 v3, v2
	v_mov_b32_e32 v4, v2
	v_mov_b32_e32 v5, v2
	v_mov_b32_e32 v6, v2
	v_mov_b32_e32 v7, v2
	v_mov_b32_e32 v8, v2
	v_mov_b32_e32 v9, v2
	v_mov_b32_e32 v14, v2
	v_mov_b32_e32 v15, v2
	v_mov_b32_e32 v16, v2
	v_mov_b32_e32 v17, v2
	v_mov_b32_e32 v22, v2
	v_mov_b32_e32 v23, v2
	v_mov_b32_e32 v24, v2
	v_mov_b32_e32 v25, v2
	v_mov_b32_e32 v30, v2
	v_mov_b32_e32 v31, v2
	v_mov_b32_e32 v32, v2
	v_mov_b32_e32 v33, v2
	v_mov_b32_e32 v38, v2
	v_mov_b32_e32 v39, v2
	v_mov_b32_e32 v40, v2
	v_mov_b32_e32 v41, v2
	v_mov_b32_e32 v46, v2
	v_mov_b32_e32 v47, v2
	v_mov_b32_e32 v48, v2
	v_mov_b32_e32 v49, v2
	v_mov_b32_e32 v54, v2
	v_mov_b32_e32 v55, v2
	v_mov_b32_e32 v56, v2
	v_mov_b32_e32 v57, v2
	v_mov_b32_e32 v10, v2
	v_mov_b32_e32 v11, v2
	v_mov_b32_e32 v12, v2
	v_mov_b32_e32 v13, v2
	v_mov_b32_e32 v18, v2
	v_mov_b32_e32 v19, v2
	v_mov_b32_e32 v20, v2
	v_mov_b32_e32 v21, v2
	v_mov_b32_e32 v26, v2
	v_mov_b32_e32 v27, v2
	v_mov_b32_e32 v28, v2
	v_mov_b32_e32 v29, v2
	v_mov_b32_e32 v34, v2
	v_mov_b32_e32 v35, v2
	v_mov_b32_e32 v36, v2
	v_mov_b32_e32 v37, v2
	v_mov_b32_e32 v42, v2
	v_mov_b32_e32 v43, v2
	v_mov_b32_e32 v44, v2
	v_mov_b32_e32 v45, v2
	v_mov_b32_e32 v50, v2
	v_mov_b32_e32 v51, v2
	v_mov_b32_e32 v52, v2
	v_mov_b32_e32 v53, v2
	v_mov_b32_e32 v58, v2
	v_mov_b32_e32 v59, v2
	v_mov_b32_e32 v60, v2
	v_mov_b32_e32 v61, v2
	v_mov_b32_e32 v62, v2
	v_mov_b32_e32 v63, v2
	v_mov_b32_e32 v64, v2
	v_mov_b32_e32 v65, v2
	v_mov_b32_e32 v66, v2
	v_mov_b32_e32 v67, v2
	v_mov_b32_e32 v68, v2
	v_mov_b32_e32 v69, v2
	v_mov_b32_e32 v70, v2
	v_mov_b32_e32 v71, v2
	v_mov_b32_e32 v72, v2
	v_mov_b32_e32 v73, v2
	v_mov_b32_e32 v78, v2
	v_mov_b32_e32 v79, v2
	v_mov_b32_e32 v80, v2
	v_mov_b32_e32 v81, v2
	v_mov_b32_e32 v86, v2
	v_mov_b32_e32 v87, v2
	v_mov_b32_e32 v88, v2
	v_mov_b32_e32 v89, v2
	v_mov_b32_e32 v94, v2
	v_mov_b32_e32 v95, v2
	v_mov_b32_e32 v96, v2
	v_mov_b32_e32 v97, v2
	v_mov_b32_e32 v102, v2
	v_mov_b32_e32 v103, v2
	v_mov_b32_e32 v104, v2
	v_mov_b32_e32 v105, v2
	v_mov_b32_e32 v110, v2
	v_mov_b32_e32 v111, v2
	v_mov_b32_e32 v112, v2
	v_mov_b32_e32 v113, v2
	v_mov_b32_e32 v118, v2
	v_mov_b32_e32 v119, v2
	v_mov_b32_e32 v120, v2
	v_mov_b32_e32 v121, v2
	v_mov_b32_e32 v74, v2
	v_mov_b32_e32 v75, v2
	v_mov_b32_e32 v76, v2
	v_mov_b32_e32 v77, v2
	v_mov_b32_e32 v82, v2
	v_mov_b32_e32 v83, v2
	v_mov_b32_e32 v84, v2
	v_mov_b32_e32 v85, v2
	v_mov_b32_e32 v90, v2
	v_mov_b32_e32 v91, v2
	v_mov_b32_e32 v92, v2
	v_mov_b32_e32 v93, v2
	v_mov_b32_e32 v98, v2
	v_mov_b32_e32 v99, v2
	v_mov_b32_e32 v100, v2
	v_mov_b32_e32 v101, v2
	v_mov_b32_e32 v106, v2
	v_mov_b32_e32 v107, v2
	v_mov_b32_e32 v108, v2
	v_mov_b32_e32 v109, v2
	v_mov_b32_e32 v114, v2
	v_mov_b32_e32 v115, v2
	v_mov_b32_e32 v116, v2
	v_mov_b32_e32 v117, v2
	v_mov_b32_e32 v122, v2
	v_mov_b32_e32 v123, v2
	v_mov_b32_e32 v124, v2
	v_mov_b32_e32 v125, v2
	v_mov_b32_e32 v126, v2
	v_mov_b32_e32 v127, v2
	v_mov_b32_e32 v128, v2
	v_mov_b32_e32 v129, v2
	s_add_i32 s30, s66, 0xffc00000
	s_and_b32 s30, s30, 0x3800000
	s_and_b32 s31, s28, 0x100
	s_or_b32 s67, s31, s30
	s_and_b32 s34, s66, 0x7800000
	s_add_u32 s30, s28, 0x100
	s_addc_u32 s31, s29, 0
	s_and_b32 s35, s30, 0x100
	s_or_b32 s34, s34, s35
	s_add_u32 s34, s26, s34
	s_addc_u32 s35, s27, 0
	s_add_u32 s28, s63, s28
	s_addc_u32 s29, s64, s29
	s_add_i32 s70, 0, 0x10000
	s_cmp_eq_u32 s65, 28
	s_cselect_b32 s35, s19, s35
	s_cselect_b32 s34, s61, s34
	v_add_u32_e32 v139, s70, v165
	s_cselect_b32 s29, s17, s29
	s_cselect_b32 s28, s62, s28
	s_add_i32 s71, 0, 0x14000
	ds_read_b128 v[152:155], v139
	ds_read_b128 v[160:163], v139 offset:1024
	ds_read_b128 v[174:177], v139 offset:2048
	ds_read_b128 v[178:181], v139 offset:3072
	v_add_u32_e32 v139, s71, v165
	ds_read_b128 v[182:185], v139
	ds_read_b128 v[186:189], v139 offset:1024
	ds_read_b128 v[190:193], v139 offset:2048
	ds_read_b128 v[194:197], v139 offset:3072
	s_add_u32 s67, s26, s67
	s_addc_u32 s69, s27, 0
	s_add_u32 s68, s67, 0x10080
	s_addc_u32 s69, s69, 0
	s_add_i32 m0, s25, 0xc000
	ds_read_b128 v[198:201], v173
	ds_read_b128 v[202:205], v173 offset:1024
	ds_read_b128 v[206:209], v173 offset:2048
	ds_read_b128 v[210:213], v173 offset:3072
	ds_read_b128 v[214:217], v173 offset:4096
	ds_read_b128 v[218:221], v173 offset:5120
	ds_read_b128 v[222:225], v173 offset:6144
	ds_read_b128 v[226:229], v173 offset:7168
	global_load_lds_dwordx4 v136, s[68:69]
	s_add_i32 m0, s25, 0xe000
	s_nop 0
	global_load_lds_dwordx4 v132, s[68:69]
	s_waitcnt vmcnt(24)
	s_waitcnt lgkmcnt(0)
	s_barrier
; #define PG8_STAGE(bufoff, gbase, voff) do { _Pragma("unroll") for (int _i = 0; _i < 2; ++_i) \
;         __builtin_amdgcn_global_load_lds((const unsigned*)((const char*)(gbase) + (voff)[_i]), (LAS unsigned*)(lds + (bufoff) + ldsw + _i * 8192), 16, 0, 0); } while (0)
; #define PG8_LDA(dst, b, h) do { _Pragma("unroll") for (int m = 0; m < 4; ++m) _Pragma("unroll") for (int k = 0; k < 2; ++k) dst[m][k] = *(const LAS bf16x8*)(lds + PG8_SA(b, h) + aoff + m * 2048 + k * 1024); } while (0)
; #define PG8_LDB(dst, b, h) do { _Pragma("unroll") for (int n = 0; n < 2; ++n) _Pragma("unroll") for (int k = 0; k < 2; ++k) dst[n][k] = *(const LAS bf16x8*)(lds + PG8_SB(b, h) + boff + n * 2048 + k * 1024); } while (0)
; #define PG8_MMA(ai, bj, At, Bt) do { __builtin_amdgcn_s_setprio(1); _Pragma("unroll") for (int m = 0; m < 4; ++m) _Pragma("unroll") for (int n = 0; n < 2; ++n) _Pragma("unroll") for (int k = 0; k < 2; ++k) \
;         acc[ai][bj][m][n] = __builtin_amdgcn_mfma_f32_16x16x32_bf16(Bt[n][k], At[m][k], acc[ai][bj][m][n], 0, 0, 0); __builtin_amdgcn_s_setprio(0); } while (0)
; #define PG8_WAIT_V(n) asm volatile("s_waitcnt vmcnt(" #n ")" ::: "memory")
; #define PG8_WAIT_L(n) asm volatile("s_waitcnt lgkmcnt(" #n ")" ::: "memory")
; #define PG8_BAR __builtin_amdgcn_s_barrier()
; #define PG8_SCHED __builtin_amdgcn_sched_barrier(0)
; template <class Epi, class Sched, int KC, bool ALIGN_EPI = false, bool SP2 = false, bool ATILED = false>
; __device__ __forceinline__ void gemm_phase(LAS unsigned char* lds, const Gemm g, const Sched& S, const Epi& E, int wave_s) {
;     ...
;             PG8_LDB(B0, 0, 0); PG8_LDB(B1, 0, 1); PG8_SCHED; PG8_LDA(At, 0, 0); PG8_STAGE(PG8_SA(1, 1), a1 + hstepA, voffA);
;             PG8_WAIT_V(8); PG8_WAIT_L(0); PG8_BAR; PG8_MMA(0, 0, At, B0); PG8_MMA(0, 1, At, B1); PG8_BAR; PG8_SCHED;
;             PG8_LDA(At, 0, 1); PG8_STAGE(PG8_SB(0, 0), b2, voffB); PG8_STAGE(PG8_SB(0, 1), b2 + hstepB, voffB); PG8_STAGE(PG8_SA(0, 0), a2, voffA);
;             PG8_WAIT_V(8); PG8_WAIT_L(0); PG8_BAR; PG8_MMA(1, 0, At, B0); PG8_MMA(1, 1, At, B1); PG8_BAR; PG8_SCHED;
	s_setprio 1
	s_waitcnt lgkmcnt(0)
	v_mfma_f32_16x16x32_bf16 v[126:129], v[152:155], v[198:201], v[126:129]
	v_mfma_f32_16x16x32_bf16 v[122:125], v[174:177], v[198:201], v[122:125]
	v_mfma_f32_16x16x32_bf16 v[114:117], v[152:155], v[206:209], v[114:117]
	v_mfma_f32_16x16x32_bf16 v[106:109], v[174:177], v[206:209], v[106:109]
	v_mfma_f32_16x16x32_bf16 v[98:101], v[152:155], v[214:217], v[98:101]
	v_mfma_f32_16x16x32_bf16 v[90:93], v[174:177], v[214:217], v[90:93]
	v_mfma_f32_16x16x32_bf16 v[82:85], v[152:155], v[222:225], v[82:85]
	v_mfma_f32_16x16x32_bf16 v[74:77], v[174:177], v[222:225], v[74:77]
	v_mfma_f32_16x16x32_bf16 v[126:129], v[160:163], v[202:205], v[126:129]
	v_mfma_f32_16x16x32_bf16 v[122:125], v[178:181], v[202:205], v[122:125]
	v_mfma_f32_16x16x32_bf16 v[114:117], v[160:163], v[210:213], v[114:117]
	v_mfma_f32_16x16x32_bf16 v[106:109], v[178:181], v[210:213], v[106:109]
	v_mfma_f32_16x16x32_bf16 v[98:101], v[160:163], v[218:221], v[98:101]
	v_mfma_f32_16x16x32_bf16 v[90:93], v[178:181], v[218:221], v[90:93]
	v_mfma_f32_16x16x32_bf16 v[82:85], v[160:163], v[226:229], v[82:85]
	v_mfma_f32_16x16x32_bf16 v[74:77], v[178:181], v[226:229], v[74:77]
	s_setprio 0
	s_setprio 1
	v_mfma_f32_16x16x32_bf16 v[118:121], v[182:185], v[198:201], v[118:121]
	v_mfma_f32_16x16x32_bf16 v[110:113], v[190:193], v[198:201], v[110:113]
	v_mfma_f32_16x16x32_bf16 v[102:105], v[182:185], v[206:209], v[102:105]
	v_mfma_f32_16x16x32_bf16 v[94:97], v[190:193], v[206:209], v[94:97]
	v_mfma_f32_16x16x32_bf16 v[86:89], v[182:185], v[214:217], v[86:89]
	v_mfma_f32_16x16x32_bf16 v[78:81], v[190:193], v[214:217], v[78:81]
	v_mfma_f32_16x16x32_bf16 v[70:73], v[182:185], v[222:225], v[70:73]
	v_mfma_f32_16x16x32_bf16 v[66:69], v[190:193], v[222:225], v[66:69]
	v_mfma_f32_16x16x32_bf16 v[118:121], v[186:189], v[202:205], v[118:121]
	v_mfma_f32_16x16x32_bf16 v[110:113], v[194:197], v[202:205], v[110:113]
	v_mfma_f32_16x16x32_bf16 v[102:105], v[186:189], v[210:213], v[102:105]
	v_mfma_f32_16x16x32_bf16 v[94:97], v[194:197], v[210:213], v[94:97]
	v_mfma_f32_16x16x32_bf16 v[86:89], v[186:189], v[218:221], v[86:89]
	v_mfma_f32_16x16x32_bf16 v[78:81], v[194:197], v[218:221], v[78:81]
	v_mfma_f32_16x16x32_bf16 v[70:73], v[186:189], v[226:229], v[70:73]
	v_mfma_f32_16x16x32_bf16 v[66:69], v[194:197], v[226:229], v[66:69]
	s_setprio 0
	s_barrier
	s_add_u32 s100, s34, 0x80
	s_addc_u32 s101, s35, 0
	s_add_i32 s67, s70, s41
	s_mov_b32 m0, s67
	ds_read_b128 v[198:201], v173 offset:16384
	ds_read_b128 v[202:205], v173 offset:17408
	ds_read_b128 v[206:209], v173 offset:18432
	ds_read_b128 v[210:213], v173 offset:19456
	ds_read_b128 v[214:217], v173 offset:20480
	ds_read_b128 v[218:221], v173 offset:21504
	ds_read_b128 v[222:225], v173 offset:22528
	ds_read_b128 v[226:229], v173 offset:23552
	global_load_lds_dwordx4 v134, s[28:29]
	s_add_i32 m0, s67, 0x2000
	s_add_u32 s68, s28, 0x80000
	s_addc_u32 s69, s29, 0
	s_add_i32 s67, s71, s41
	global_load_lds_dwordx4 v130, s[28:29]
	s_mov_b32 m0, s67
	s_nop 0
	global_load_lds_dwordx4 v134, s[68:69]
	s_add_i32 m0, s67, 0x2000
	s_nop 0
	global_load_lds_dwordx4 v130, s[68:69]
	s_mov_b32 m0, s25
	s_nop 0
	global_load_lds_dwordx4 v136, s[34:35]
	s_mov_b32 m0, s52
	s_nop 0
	global_load_lds_dwordx4 v132, s[34:35]
	s_waitcnt vmcnt(24)
	s_waitcnt lgkmcnt(0)
	s_barrier
	s_setprio 1
	s_waitcnt lgkmcnt(0)
	v_mfma_f32_16x16x32_bf16 v[62:65], v[152:155], v[198:201], v[62:65]
	v_mfma_f32_16x16x32_bf16 v[58:61], v[174:177], v[198:201], v[58:61]
	v_mfma_f32_16x16x32_bf16 v[50:53], v[152:155], v[206:209], v[50:53]
	v_mfma_f32_16x16x32_bf16 v[42:45], v[174:177], v[206:209], v[42:45]
	v_mfma_f32_16x16x32_bf16 v[34:37], v[152:155], v[214:217], v[34:37]
	v_mfma_f32_16x16x32_bf16 v[26:29], v[174:177], v[214:217], v[26:29]
	v_mfma_f32_16x16x32_bf16 v[18:21], v[152:155], v[222:225], v[18:21]
	v_mfma_f32_16x16x32_bf16 v[10:13], v[174:177], v[222:225], v[10:13]
	v_mfma_f32_16x16x32_bf16 v[62:65], v[160:163], v[202:205], v[62:65]
	v_mfma_f32_16x16x32_bf16 v[58:61], v[178:181], v[202:205], v[58:61]
	v_mfma_f32_16x16x32_bf16 v[50:53], v[160:163], v[210:213], v[50:53]
	v_mfma_f32_16x16x32_bf16 v[42:45], v[178:181], v[210:213], v[42:45]
	v_mfma_f32_16x16x32_bf16 v[34:37], v[160:163], v[218:221], v[34:37]
	v_mfma_f32_16x16x32_bf16 v[26:29], v[178:181], v[218:221], v[26:29]
	v_mfma_f32_16x16x32_bf16 v[18:21], v[160:163], v[226:229], v[18:21]
	v_mfma_f32_16x16x32_bf16 v[10:13], v[178:181], v[226:229], v[10:13]
	s_setprio 0
	s_setprio 1
	v_mfma_f32_16x16x32_bf16 v[54:57], v[182:185], v[198:201], v[54:57]
	v_mfma_f32_16x16x32_bf16 v[46:49], v[190:193], v[198:201], v[46:49]
	v_mfma_f32_16x16x32_bf16 v[38:41], v[182:185], v[206:209], v[38:41]
	v_mfma_f32_16x16x32_bf16 v[30:33], v[190:193], v[206:209], v[30:33]
	v_mfma_f32_16x16x32_bf16 v[22:25], v[182:185], v[214:217], v[22:25]
	v_mfma_f32_16x16x32_bf16 v[14:17], v[190:193], v[214:217], v[14:17]
	v_mfma_f32_16x16x32_bf16 v[6:9], v[182:185], v[222:225], v[6:9]
	v_mfma_f32_16x16x32_bf16 v[2:5], v[190:193], v[222:225], v[2:5]
	v_mfma_f32_16x16x32_bf16 v[54:57], v[186:189], v[202:205], v[54:57]
	v_mfma_f32_16x16x32_bf16 v[46:49], v[194:197], v[202:205], v[46:49]
	v_mfma_f32_16x16x32_bf16 v[38:41], v[186:189], v[210:213], v[38:41]
	v_mfma_f32_16x16x32_bf16 v[30:33], v[194:197], v[210:213], v[30:33]
	v_mfma_f32_16x16x32_bf16 v[22:25], v[186:189], v[218:221], v[22:25]
	v_mfma_f32_16x16x32_bf16 v[14:17], v[194:197], v[218:221], v[14:17]
	v_mfma_f32_16x16x32_bf16 v[6:9], v[186:189], v[226:229], v[6:9]
	v_mfma_f32_16x16x32_bf16 v[2:5], v[194:197], v[226:229], v[2:5]
	s_setprio 0
	s_barrier
; #define PG8_STAGE(bufoff, gbase, voff) do { _Pragma("unroll") for (int _i = 0; _i < 2; ++_i) \
;         __builtin_amdgcn_global_load_lds((const unsigned*)((const char*)(gbase) + (voff)[_i]), (LAS unsigned*)(lds + (bufoff) + ldsw + _i * 8192), 16, 0, 0); } while (0)
; #define PG8_LDA(dst, b, h) do { _Pragma("unroll") for (int m = 0; m < 4; ++m) _Pragma("unroll") for (int k = 0; k < 2; ++k) dst[m][k] = *(const LAS bf16x8*)(lds + PG8_SA(b, h) + aoff + m * 2048 + k * 1024); } while (0)
; #define PG8_LDB(dst, b, h) do { _Pragma("unroll") for (int n = 0; n < 2; ++n) _Pragma("unroll") for (int k = 0; k < 2; ++k) dst[n][k] = *(const LAS bf16x8*)(lds + PG8_SB(b, h) + boff + n * 2048 + k * 1024); } while (0)
; #define PG8_MMA(ai, bj, At, Bt) do { __builtin_amdgcn_s_setprio(1); _Pragma("unroll") for (int m = 0; m < 4; ++m) _Pragma("unroll") for (int n = 0; n < 2; ++n) _Pragma("unroll") for (int k = 0; k < 2; ++k) \
;         acc[ai][bj][m][n] = __builtin_amdgcn_mfma_f32_16x16x32_bf16(Bt[n][k], At[m][k], acc[ai][bj][m][n], 0, 0, 0); __builtin_amdgcn_s_setprio(0); } while (0)
; #define PG8_WAIT_V(n) asm volatile("s_waitcnt vmcnt(" #n ")" ::: "memory")
; #define PG8_WAIT_L(n) asm volatile("s_waitcnt lgkmcnt(" #n ")" ::: "memory")
; #define PG8_BAR __builtin_amdgcn_s_barrier()
; #define PG8_SCHED __builtin_amdgcn_sched_barrier(0)
; template <class Epi, class Sched, int KC, bool ALIGN_EPI = false, bool SP2 = false, bool ATILED = false>
; __device__ __forceinline__ void gemm_phase(LAS unsigned char* lds, const Gemm g, const Sched& S, const Epi& E, int wave_s) {
;     ...
;             PG8_LDB(B0, 1, 0); PG8_LDB(B1, 1, 1); PG8_SCHED; PG8_LDA(At, 1, 0); PG8_STAGE(PG8_SA(0, 1), a2 + hstepA, voffA);
;             PG8_WAIT_V(8); PG8_WAIT_L(0); PG8_BAR; PG8_MMA(0, 0, At, B0); PG8_MMA(0, 1, At, B1); PG8_BAR; PG8_SCHED;
;             PG8_LDA(At, 1, 1); PG8_STAGE(PG8_SB(1, 0), b3, voffB); PG8_STAGE(PG8_SB(1, 1), b3 + hstepB, voffB); PG8_STAGE(PG8_SA(1, 0), a3, voffA);
;             PG8_WAIT_V(8); PG8_WAIT_L(0); PG8_BAR; PG8_MMA(1, 0, At, B0); PG8_MMA(1, 1, At, B1); PG8_BAR; PG8_SCHED;
	s_add_i32 s67, 0, 0x18000
	v_add_u32_e32 v139, s67, v165
	s_add_i32 s68, 0, 0x1c000
	ds_read_b128 v[152:155], v139
	ds_read_b128 v[160:163], v139 offset:1024
	ds_read_b128 v[174:177], v139 offset:2048
	ds_read_b128 v[178:181], v139 offset:3072
	v_add_u32_e32 v139, s68, v165
	ds_read_b128 v[182:185], v139
	ds_read_b128 v[186:189], v139 offset:1024
	ds_read_b128 v[190:193], v139 offset:2048
	ds_read_b128 v[194:197], v139 offset:3072
	s_add_u32 s34, s34, 0x10000
	s_addc_u32 s35, s35, 0
	s_mov_b32 m0, s53
	ds_read_b128 v[198:201], v173 offset:32768
	ds_read_b128 v[202:205], v173 offset:33792
	ds_read_b128 v[206:209], v173 offset:34816
	ds_read_b128 v[210:213], v173 offset:35840
	ds_read_b128 v[214:217], v173 offset:36864
	ds_read_b128 v[218:221], v173 offset:37888
	ds_read_b128 v[222:225], v173 offset:38912
	ds_read_b128 v[226:229], v173 offset:39936
	global_load_lds_dwordx4 v136, s[34:35]
	s_mov_b32 m0, s54
	s_nop 0
	global_load_lds_dwordx4 v132, s[34:35]
	s_waitcnt vmcnt(8)
	s_waitcnt lgkmcnt(0)
	s_barrier
	s_setprio 1
	s_waitcnt lgkmcnt(0)
	v_mfma_f32_16x16x32_bf16 v[126:129], v[152:155], v[198:201], v[126:129]
	v_mfma_f32_16x16x32_bf16 v[122:125], v[174:177], v[198:201], v[122:125]
	v_mfma_f32_16x16x32_bf16 v[114:117], v[152:155], v[206:209], v[114:117]
	v_mfma_f32_16x16x32_bf16 v[106:109], v[174:177], v[206:209], v[106:109]
	v_mfma_f32_16x16x32_bf16 v[98:101], v[152:155], v[214:217], v[98:101]
	v_mfma_f32_16x16x32_bf16 v[90:93], v[174:177], v[214:217], v[90:93]
	v_mfma_f32_16x16x32_bf16 v[82:85], v[152:155], v[222:225], v[82:85]
	v_mfma_f32_16x16x32_bf16 v[74:77], v[174:177], v[222:225], v[74:77]
	v_mfma_f32_16x16x32_bf16 v[126:129], v[160:163], v[202:205], v[126:129]
	v_mfma_f32_16x16x32_bf16 v[122:125], v[178:181], v[202:205], v[122:125]
	v_mfma_f32_16x16x32_bf16 v[114:117], v[160:163], v[210:213], v[114:117]
	v_mfma_f32_16x16x32_bf16 v[106:109], v[178:181], v[210:213], v[106:109]
	v_mfma_f32_16x16x32_bf16 v[98:101], v[160:163], v[218:221], v[98:101]
	v_mfma_f32_16x16x32_bf16 v[90:93], v[178:181], v[218:221], v[90:93]
	v_mfma_f32_16x16x32_bf16 v[82:85], v[160:163], v[226:229], v[82:85]
	v_mfma_f32_16x16x32_bf16 v[74:77], v[178:181], v[226:229], v[74:77]
	s_setprio 0
	s_setprio 1
	v_mfma_f32_16x16x32_bf16 v[118:121], v[182:185], v[198:201], v[118:121]
	v_mfma_f32_16x16x32_bf16 v[110:113], v[190:193], v[198:201], v[110:113]
	v_mfma_f32_16x16x32_bf16 v[102:105], v[182:185], v[206:209], v[102:105]
	v_mfma_f32_16x16x32_bf16 v[94:97], v[190:193], v[206:209], v[94:97]
	v_mfma_f32_16x16x32_bf16 v[86:89], v[182:185], v[214:217], v[86:89]
	v_mfma_f32_16x16x32_bf16 v[78:81], v[190:193], v[214:217], v[78:81]
	v_mfma_f32_16x16x32_bf16 v[70:73], v[182:185], v[222:225], v[70:73]
	v_mfma_f32_16x16x32_bf16 v[66:69], v[190:193], v[222:225], v[66:69]
	v_mfma_f32_16x16x32_bf16 v[118:121], v[186:189], v[202:205], v[118:121]
	v_mfma_f32_16x16x32_bf16 v[110:113], v[194:197], v[202:205], v[110:113]
	v_mfma_f32_16x16x32_bf16 v[102:105], v[186:189], v[210:213], v[102:105]
	v_mfma_f32_16x16x32_bf16 v[94:97], v[194:197], v[210:213], v[94:97]
	v_mfma_f32_16x16x32_bf16 v[86:89], v[186:189], v[218:221], v[86:89]
	v_mfma_f32_16x16x32_bf16 v[78:81], v[194:197], v[218:221], v[78:81]
	v_mfma_f32_16x16x32_bf16 v[70:73], v[186:189], v[226:229], v[70:73]
	v_mfma_f32_16x16x32_bf16 v[66:69], v[194:197], v[226:229], v[66:69]
	s_setprio 0
	s_barrier
	s_add_u32 s98, s28, 0x80
	s_addc_u32 s99, s29, 0
	s_add_i32 s34, s67, s41
	s_mov_b32 m0, s34
	ds_read_b128 v[198:201], v173 offset:49152
	ds_read_b128 v[202:205], v173 offset:50176
	ds_read_b128 v[206:209], v173 offset:51200
	ds_read_b128 v[210:213], v173 offset:52224
	ds_read_b128 v[214:217], v173 offset:53248
	ds_read_b128 v[218:221], v173 offset:54272
	ds_read_b128 v[222:225], v173 offset:55296
	ds_read_b128 v[226:229], v173 offset:56320
	global_load_lds_dwordx4 v134, s[98:99]
	s_add_i32 m0, s34, 0x2000
	s_add_u32 s28, s28, 0x80080
	s_addc_u32 s29, s29, 0
	s_add_i32 s34, s68, s41
	global_load_lds_dwordx4 v130, s[98:99]
	s_mov_b32 m0, s34
	s_nop 0
	global_load_lds_dwordx4 v134, s[28:29]
	s_add_i32 m0, s34, 0x2000
	s_nop 0
	global_load_lds_dwordx4 v130, s[28:29]
	s_mov_b32 m0, s55
	s_nop 0
	global_load_lds_dwordx4 v136, s[100:101]
	s_mov_b32 m0, s56
	s_nop 0
	global_load_lds_dwordx4 v132, s[100:101]
	s_waitcnt vmcnt(8)
	s_waitcnt lgkmcnt(0)
	s_barrier
	s_setprio 1
	s_waitcnt lgkmcnt(0)
	v_mfma_f32_16x16x32_bf16 v[62:65], v[152:155], v[198:201], v[62:65]
	v_mfma_f32_16x16x32_bf16 v[58:61], v[174:177], v[198:201], v[58:61]
	v_mfma_f32_16x16x32_bf16 v[50:53], v[152:155], v[206:209], v[50:53]
	v_mfma_f32_16x16x32_bf16 v[42:45], v[174:177], v[206:209], v[42:45]
	v_mfma_f32_16x16x32_bf16 v[34:37], v[152:155], v[214:217], v[34:37]
	v_mfma_f32_16x16x32_bf16 v[26:29], v[174:177], v[214:217], v[26:29]
	v_mfma_f32_16x16x32_bf16 v[18:21], v[152:155], v[222:225], v[18:21]
	v_mfma_f32_16x16x32_bf16 v[10:13], v[174:177], v[222:225], v[10:13]
	v_mfma_f32_16x16x32_bf16 v[62:65], v[160:163], v[202:205], v[62:65]
	v_mfma_f32_16x16x32_bf16 v[58:61], v[178:181], v[202:205], v[58:61]
	v_mfma_f32_16x16x32_bf16 v[50:53], v[160:163], v[210:213], v[50:53]
	v_mfma_f32_16x16x32_bf16 v[42:45], v[178:181], v[210:213], v[42:45]
	v_mfma_f32_16x16x32_bf16 v[34:37], v[160:163], v[218:221], v[34:37]
	v_mfma_f32_16x16x32_bf16 v[26:29], v[178:181], v[218:221], v[26:29]
	v_mfma_f32_16x16x32_bf16 v[18:21], v[160:163], v[226:229], v[18:21]
	v_mfma_f32_16x16x32_bf16 v[10:13], v[178:181], v[226:229], v[10:13]
	s_setprio 0
	s_setprio 1
	v_mfma_f32_16x16x32_bf16 v[54:57], v[182:185], v[198:201], v[54:57]
	v_mfma_f32_16x16x32_bf16 v[46:49], v[190:193], v[198:201], v[46:49]
	v_mfma_f32_16x16x32_bf16 v[38:41], v[182:185], v[206:209], v[38:41]
	v_mfma_f32_16x16x32_bf16 v[30:33], v[190:193], v[206:209], v[30:33]
	v_mfma_f32_16x16x32_bf16 v[22:25], v[182:185], v[214:217], v[22:25]
	v_mfma_f32_16x16x32_bf16 v[14:17], v[190:193], v[214:217], v[14:17]
	v_mfma_f32_16x16x32_bf16 v[6:9], v[182:185], v[222:225], v[6:9]
	v_mfma_f32_16x16x32_bf16 v[2:5], v[190:193], v[222:225], v[2:5]
	v_mfma_f32_16x16x32_bf16 v[54:57], v[186:189], v[202:205], v[54:57]
	v_mfma_f32_16x16x32_bf16 v[46:49], v[194:197], v[202:205], v[46:49]
	v_mfma_f32_16x16x32_bf16 v[38:41], v[186:189], v[210:213], v[38:41]
	v_mfma_f32_16x16x32_bf16 v[30:33], v[194:197], v[210:213], v[30:33]
	v_mfma_f32_16x16x32_bf16 v[22:25], v[186:189], v[218:221], v[22:25]
	v_mfma_f32_16x16x32_bf16 v[14:17], v[194:197], v[218:221], v[14:17]
	v_mfma_f32_16x16x32_bf16 v[6:9], v[186:189], v[226:229], v[6:9]
	v_mfma_f32_16x16x32_bf16 v[2:5], v[194:197], v[226:229], v[2:5]
	s_setprio 0
	s_barrier
	s_add_i32 s65, s65, 2
	s_add_i32 s66, s66, 0x400000
	s_cmp_gt_u32 s65, 29
	s_mov_b64 s[28:29], s[30:31]

; #define PG8_STAGE(bufoff, gbase, voff) do { _Pragma("unroll") for (int _i = 0; _i < 2; ++_i) \
;         __builtin_amdgcn_global_load_lds((const unsigned*)((const char*)(gbase) + (voff)[_i]), (LAS unsigned*)(lds + (bufoff) + ldsw + _i * 8192), 16, 0, 0); } while (0)
; #define PG8_LDA(dst, b, h) do { _Pragma("unroll") for (int m = 0; m < 4; ++m) _Pragma("unroll") for (int k = 0; k < 2; ++k) dst[m][k] = *(const LAS bf16x8*)(lds + PG8_SA(b, h) + aoff + m * 2048 + k * 1024); } while (0)
; #define PG8_LDB(dst, b, h) do { _Pragma("unroll") for (int n = 0; n < 2; ++n) _Pragma("unroll") for (int k = 0; k < 2; ++k) dst[n][k] = *(const LAS bf16x8*)(lds + PG8_SB(b, h) + boff + n * 2048 + k * 1024); } while (0)
; #define PG8_WAIT_V(n) asm volatile("s_waitcnt vmcnt(" #n ")" ::: "memory")
; #define PG8_WAIT_L(n) asm volatile("s_waitcnt lgkmcnt(" #n ")" ::: "memory")
; #define PG8_BAR __builtin_amdgcn_s_barrier()
; template <class Epi, class Sched, int KC, bool ALIGN_EPI = false, bool SP2 = false, bool ATILED = false>
; __device__ __forceinline__ void gemm_phase(LAS unsigned char* lds, const Gemm g, const Sched& S, const Epi& E, int wave_s) {
;     ...
;         const bool has_next = S.next(ui + 1, nxt);
;         const char* nA = has_next ? (const char*)g.A + (size_t)nxt.pm * tstepA : cA; const char* nB = has_next ? (const char*)g.Bt + (size_t)nxt.pn * tstep : cB;
;         for (int t = 0; t < nt; t += 2) {
;             const bool last = (t == nt - 2);
;             const char* a1 = cA + PG8_AOFF(t + 1);
;             const char* a2 = last ? nA : cA + PG8_AOFF(t + 2); const char* b2 = last ? nB : cB + (size_t)(t + 2) * kstep;
;             const char* a3 = a2 + kstep; const char* b3 = b2 + kstep;
;             if (last && has_next) S.a_ready(nxt);
;             if constexpr (SP2) {
;             PG8_LDB(B0, 0, 0); PG8_LDB(B1, 0, 1); PG8_SCHED; PG8_LDA(At, 0, 0); PG8_STAGE(PG8_SA(1, 1), a1 + hstepA, voffA);
;             PG8_WAIT_V(8); PG8_WAIT_L(0); PG8_BAR; PG8_MMA(0, 0, At, B0); PG8_MMA(0, 1, At, B1); PG8_BAR; PG8_SCHED;
;     ...
; #pragma unroll
;         for (int a = 0; a < 2; ++a)
; #pragma unroll
;             for (int b = 0; b < 2; ++b)
; #pragma unroll
;                 for (int m = 0; m < 4; ++m)
; #pragma unroll
;                     for (int n = 0; n < 2; ++n) acc[a][b][m][n] = (f32x4){0.f, 0.f, 0.f, 0.f};
;         cur = nxt; cA = nA; cB = nB; ++ui;
.LBB0_1020:
	v_mov_b64_e32 v[2:3], 0x200
	s_ashr_i32 s9, s8, 31
	v_cmp_lt_i64_e32 vcc, s[10:11], v[2:3]
	s_lshl_b64 s[10:11], s[8:9], 20
	s_add_u32 s10, s27, s10
	s_addc_u32 s11, s28, s11
	s_and_b64 s[12:13], vcc, exec
	s_cselect_b32 s9, s11, s21
	s_cselect_b32 s15, s10, s20
	s_ashr_i32 s3, s2, 31
	s_lshl_b64 s[12:13], s[2:3], 20
	s_add_u32 s12, s29, s12
	s_addc_u32 s13, s30, s13
	s_and_b64 s[22:23], vcc, exec
	s_cselect_b32 s3, s13, s19
	s_cselect_b32 s17, s12, s18
	s_add_u32 s46, s18, 0x100
	s_addc_u32 s47, s19, 0
	s_add_u32 s18, s20, 0x80080
	v_mov_b32_e32 v2, 0
	s_addc_u32 s19, s21, 0
	s_mov_b32 s48, -2
	v_mov_b32_e32 v3, v2
	v_mov_b32_e32 v4, v2
	v_mov_b32_e32 v5, v2
	v_mov_b32_e32 v6, v2
	v_mov_b32_e32 v7, v2
	v_mov_b32_e32 v8, v2
	v_mov_b32_e32 v9, v2
	v_mov_b32_e32 v18, v2
	v_mov_b32_e32 v19, v2
	v_mov_b32_e32 v20, v2
	v_mov_b32_e32 v21, v2
	v_mov_b32_e32 v22, v2
	v_mov_b32_e32 v23, v2
	v_mov_b32_e32 v24, v2
	v_mov_b32_e32 v25, v2
	v_mov_b32_e32 v34, v2
	v_mov_b32_e32 v35, v2
	v_mov_b32_e32 v36, v2
	v_mov_b32_e32 v37, v2
	v_mov_b32_e32 v38, v2
	v_mov_b32_e32 v39, v2
	v_mov_b32_e32 v40, v2
	v_mov_b32_e32 v41, v2
	v_mov_b32_e32 v50, v2
	v_mov_b32_e32 v51, v2
	v_mov_b32_e32 v52, v2
	v_mov_b32_e32 v53, v2
	v_mov_b32_e32 v54, v2
	v_mov_b32_e32 v55, v2
	v_mov_b32_e32 v56, v2
	v_mov_b32_e32 v57, v2
	v_mov_b32_e32 v10, v2
	v_mov_b32_e32 v11, v2
	v_mov_b32_e32 v12, v2
	v_mov_b32_e32 v13, v2
	v_mov_b32_e32 v14, v2
	v_mov_b32_e32 v15, v2
	v_mov_b32_e32 v16, v2
	v_mov_b32_e32 v17, v2
	v_mov_b32_e32 v26, v2
	v_mov_b32_e32 v27, v2
	v_mov_b32_e32 v28, v2
	v_mov_b32_e32 v29, v2
	v_mov_b32_e32 v30, v2
	v_mov_b32_e32 v31, v2
	v_mov_b32_e32 v32, v2
	v_mov_b32_e32 v33, v2
	v_mov_b32_e32 v42, v2
	v_mov_b32_e32 v43, v2
	v_mov_b32_e32 v44, v2
	v_mov_b32_e32 v45, v2
	v_mov_b32_e32 v46, v2
	v_mov_b32_e32 v47, v2
	v_mov_b32_e32 v48, v2
	v_mov_b32_e32 v49, v2
	v_mov_b32_e32 v58, v2
	v_mov_b32_e32 v59, v2
	v_mov_b32_e32 v60, v2
	v_mov_b32_e32 v61, v2
	v_mov_b32_e32 v62, v2
	v_mov_b32_e32 v63, v2
	v_mov_b32_e32 v64, v2
	v_mov_b32_e32 v65, v2
	v_mov_b32_e32 v66, v2
	v_mov_b32_e32 v67, v2
	v_mov_b32_e32 v68, v2
	v_mov_b32_e32 v69, v2
	v_mov_b32_e32 v70, v2
	v_mov_b32_e32 v71, v2
	v_mov_b32_e32 v72, v2
	v_mov_b32_e32 v73, v2
	s_waitcnt vmcnt(0)
	v_mov_b32_e32 v82, v2
	v_mov_b32_e32 v83, v2
	v_mov_b32_e32 v84, v2
	v_mov_b32_e32 v85, v2
	v_mov_b32_e32 v86, v2
	v_mov_b32_e32 v87, v2
	v_mov_b32_e32 v88, v2
	v_mov_b32_e32 v89, v2
	v_mov_b32_e32 v98, v2
	v_mov_b32_e32 v99, v2
	v_mov_b32_e32 v100, v2
	v_mov_b32_e32 v101, v2
	v_mov_b32_e32 v102, v2
	v_mov_b32_e32 v103, v2
	v_mov_b32_e32 v104, v2
	v_mov_b32_e32 v105, v2
	v_mov_b32_e32 v114, v2
	v_mov_b32_e32 v115, v2
	v_mov_b32_e32 v116, v2
	v_mov_b32_e32 v117, v2
	v_mov_b32_e32 v118, v2
	v_mov_b32_e32 v119, v2
	v_mov_b32_e32 v120, v2
	v_mov_b32_e32 v121, v2
	v_mov_b32_e32 v74, v2
	v_mov_b32_e32 v75, v2
	v_mov_b32_e32 v76, v2
	v_mov_b32_e32 v77, v2
	v_mov_b32_e32 v78, v2
	v_mov_b32_e32 v79, v2
	v_mov_b32_e32 v80, v2
	v_mov_b32_e32 v81, v2
	v_mov_b32_e32 v90, v2
	v_mov_b32_e32 v91, v2
	v_mov_b32_e32 v92, v2
	v_mov_b32_e32 v93, v2
	v_mov_b32_e32 v94, v2
	v_mov_b32_e32 v95, v2
	v_mov_b32_e32 v96, v2
	v_mov_b32_e32 v97, v2
	v_mov_b32_e32 v106, v2
	v_mov_b32_e32 v107, v2
	v_mov_b32_e32 v108, v2
	v_mov_b32_e32 v109, v2
	v_mov_b32_e32 v110, v2
	v_mov_b32_e32 v111, v2
	v_mov_b32_e32 v112, v2
	v_mov_b32_e32 v113, v2
	v_mov_b32_e32 v122, v2
	v_mov_b32_e32 v123, v2
	v_mov_b32_e32 v124, v2
	v_mov_b32_e32 v125, v2
	v_mov_b32_e32 v126, v2
	v_mov_b32_e32 v127, v2
	v_mov_b32_e32 v128, v2
	v_mov_b32_e32 v129, v2
	s_add_u32 s20, s18, 0xfff80080
	s_addc_u32 s21, s19, -1
	s_add_i32 s49, 0, 0x10000
	s_cmp_eq_u32 s48, 28
	s_cselect_b32 s23, s9, s21
	s_cselect_b32 s22, s15, s20
	s_cselect_b32 s21, s3, s47
	s_cselect_b32 s20, s17, s46
	s_add_i32 s52, 0, 0x14000
	v_add_u32_e32 v142, s49, v229
	v_add_u32_e32 v158, s52, v229
	ds_read_b128 v[130:133], v142
	ds_read_b128 v[134:137], v142 offset:1024
	ds_read_b128 v[138:141], v142 offset:2048
	ds_read_b128 v[142:145], v142 offset:3072
	ds_read_b128 v[146:149], v158
	ds_read_b128 v[150:153], v158 offset:1024
	ds_read_b128 v[154:157], v158 offset:2048
	ds_read_b128 v[158:161], v158 offset:3072
	s_add_i32 m0, s34, 0xc000
	ds_read_b128 v[162:165], v230
	ds_read_b128 v[166:169], v230 offset:1024
	ds_read_b128 v[170:173], v230 offset:2048
	ds_read_b128 v[174:177], v230 offset:3072
	ds_read_b128 v[178:181], v230 offset:4096
	ds_read_b128 v[182:185], v230 offset:5120
	ds_read_b128 v[186:189], v230 offset:6144
	ds_read_b128 v[190:193], v230 offset:7168
	global_load_lds_dwordx4 v208, s[18:19]
	s_add_i32 m0, s34, 0xe000
	s_nop 0
	global_load_lds_dwordx4 v206, s[18:19]
	s_waitcnt vmcnt(32)
	s_waitcnt lgkmcnt(0)
	s_barrier
; #define PG8_STAGE(bufoff, gbase, voff) do { _Pragma("unroll") for (int _i = 0; _i < 2; ++_i) \
;         __builtin_amdgcn_global_load_lds((const unsigned*)((const char*)(gbase) + (voff)[_i]), (LAS unsigned*)(lds + (bufoff) + ldsw + _i * 8192), 16, 0, 0); } while (0)
; #define PG8_LDA(dst, b, h) do { _Pragma("unroll") for (int m = 0; m < 4; ++m) _Pragma("unroll") for (int k = 0; k < 2; ++k) dst[m][k] = *(const LAS bf16x8*)(lds + PG8_SA(b, h) + aoff + m * 2048 + k * 1024); } while (0)
; #define PG8_LDB(dst, b, h) do { _Pragma("unroll") for (int n = 0; n < 2; ++n) _Pragma("unroll") for (int k = 0; k < 2; ++k) dst[n][k] = *(const LAS bf16x8*)(lds + PG8_SB(b, h) + boff + n * 2048 + k * 1024); } while (0)
; #define PG8_MMA(ai, bj, At, Bt) do { __builtin_amdgcn_s_setprio(1); _Pragma("unroll") for (int m = 0; m < 4; ++m) _Pragma("unroll") for (int n = 0; n < 2; ++n) _Pragma("unroll") for (int k = 0; k < 2; ++k) \
;         acc[ai][bj][m][n] = __builtin_amdgcn_mfma_f32_16x16x32_bf16(Bt[n][k], At[m][k], acc[ai][bj][m][n], 0, 0, 0); __builtin_amdgcn_s_setprio(0); } while (0)
; #define PG8_WAIT_V(n) asm volatile("s_waitcnt vmcnt(" #n ")" ::: "memory")
; #define PG8_WAIT_L(n) asm volatile("s_waitcnt lgkmcnt(" #n ")" ::: "memory")
; #define PG8_BAR __builtin_amdgcn_s_barrier()
; #define PG8_SCHED __builtin_amdgcn_sched_barrier(0)
; template <class Epi, class Sched, int KC, bool ALIGN_EPI = false, bool SP2 = false, bool ATILED = false>
; __device__ __forceinline__ void gemm_phase(LAS unsigned char* lds, const Gemm g, const Sched& S, const Epi& E, int wave_s) {
;     ...
;             PG8_LDB(B0, 0, 0); PG8_LDB(B1, 0, 1); PG8_SCHED; PG8_LDA(At, 0, 0); PG8_STAGE(PG8_SA(1, 1), a1 + hstepA, voffA);
;             PG8_WAIT_V(8); PG8_WAIT_L(0); PG8_BAR; PG8_MMA(0, 0, At, B0); PG8_MMA(0, 1, At, B1); PG8_BAR; PG8_SCHED;
;             PG8_LDA(At, 0, 1); PG8_STAGE(PG8_SB(0, 0), b2, voffB); PG8_STAGE(PG8_SB(0, 1), b2 + hstepB, voffB); PG8_STAGE(PG8_SA(0, 0), a2, voffA);
;             PG8_WAIT_V(8); PG8_WAIT_L(0); PG8_BAR; PG8_MMA(1, 0, At, B0); PG8_MMA(1, 1, At, B1); PG8_BAR; PG8_SCHED;
	s_setprio 1
	s_waitcnt lgkmcnt(0)
	v_mfma_f32_16x16x32_bf16 v[126:129], v[130:133], v[162:165], v[126:129]
	v_mfma_f32_16x16x32_bf16 v[122:125], v[138:141], v[162:165], v[122:125]
	v_mfma_f32_16x16x32_bf16 v[110:113], v[130:133], v[170:173], v[110:113]
	v_mfma_f32_16x16x32_bf16 v[106:109], v[138:141], v[170:173], v[106:109]
	v_mfma_f32_16x16x32_bf16 v[94:97], v[130:133], v[178:181], v[94:97]
	v_mfma_f32_16x16x32_bf16 v[90:93], v[138:141], v[178:181], v[90:93]
	v_mfma_f32_16x16x32_bf16 v[78:81], v[130:133], v[186:189], v[78:81]
	v_mfma_f32_16x16x32_bf16 v[74:77], v[138:141], v[186:189], v[74:77]
	v_mfma_f32_16x16x32_bf16 v[126:129], v[134:137], v[166:169], v[126:129]
	v_mfma_f32_16x16x32_bf16 v[122:125], v[142:145], v[166:169], v[122:125]
	v_mfma_f32_16x16x32_bf16 v[110:113], v[134:137], v[174:177], v[110:113]
	v_mfma_f32_16x16x32_bf16 v[106:109], v[142:145], v[174:177], v[106:109]
	v_mfma_f32_16x16x32_bf16 v[94:97], v[134:137], v[182:185], v[94:97]
	v_mfma_f32_16x16x32_bf16 v[90:93], v[142:145], v[182:185], v[90:93]
	v_mfma_f32_16x16x32_bf16 v[78:81], v[134:137], v[190:193], v[78:81]
	v_mfma_f32_16x16x32_bf16 v[74:77], v[142:145], v[190:193], v[74:77]
	s_setprio 0
	s_setprio 1
	v_mfma_f32_16x16x32_bf16 v[118:121], v[146:149], v[162:165], v[118:121]
	v_mfma_f32_16x16x32_bf16 v[114:117], v[154:157], v[162:165], v[114:117]
	v_mfma_f32_16x16x32_bf16 v[102:105], v[146:149], v[170:173], v[102:105]
	v_mfma_f32_16x16x32_bf16 v[98:101], v[154:157], v[170:173], v[98:101]
	v_mfma_f32_16x16x32_bf16 v[86:89], v[146:149], v[178:181], v[86:89]
	v_mfma_f32_16x16x32_bf16 v[82:85], v[154:157], v[178:181], v[82:85]
	v_mfma_f32_16x16x32_bf16 v[70:73], v[146:149], v[186:189], v[70:73]
	v_mfma_f32_16x16x32_bf16 v[66:69], v[154:157], v[186:189], v[66:69]
	v_mfma_f32_16x16x32_bf16 v[118:121], v[150:153], v[166:169], v[118:121]
	v_mfma_f32_16x16x32_bf16 v[114:117], v[158:161], v[166:169], v[114:117]
	v_mfma_f32_16x16x32_bf16 v[102:105], v[150:153], v[174:177], v[102:105]
	v_mfma_f32_16x16x32_bf16 v[98:101], v[158:161], v[174:177], v[98:101]
	v_mfma_f32_16x16x32_bf16 v[86:89], v[150:153], v[182:185], v[86:89]
	v_mfma_f32_16x16x32_bf16 v[82:85], v[158:161], v[182:185], v[82:85]
	v_mfma_f32_16x16x32_bf16 v[70:73], v[150:153], v[190:193], v[70:73]
	v_mfma_f32_16x16x32_bf16 v[66:69], v[158:161], v[190:193], v[66:69]
	s_setprio 0
	s_barrier
	s_add_u32 s100, s22, 0x80
	s_addc_u32 s101, s23, 0
	s_add_i32 s49, s49, s31
	s_mov_b32 m0, s49
	ds_read_b128 v[162:165], v230 offset:16384
	ds_read_b128 v[166:169], v230 offset:17408
	ds_read_b128 v[170:173], v230 offset:18432
	ds_read_b128 v[174:177], v230 offset:19456
	ds_read_b128 v[178:181], v230 offset:20480
	ds_read_b128 v[182:185], v230 offset:21504
	ds_read_b128 v[186:189], v230 offset:22528
	ds_read_b128 v[190:193], v230 offset:23552
	global_load_lds_dwordx4 v0, s[20:21]
	s_add_i32 m0, s49, 0x2000
	s_add_u32 s50, s20, 0x20000
	s_addc_u32 s51, s21, 0
	s_add_i32 s49, s52, s31
	global_load_lds_dwordx4 v202, s[20:21]
	s_mov_b32 m0, s49
	s_nop 0
	global_load_lds_dwordx4 v0, s[50:51]
	s_add_i32 m0, s49, 0x2000
	s_nop 0
	global_load_lds_dwordx4 v202, s[50:51]
	s_mov_b32 m0, s34
	s_nop 0
	global_load_lds_dwordx4 v198, s[22:23]
	s_mov_b32 m0, s35
	s_nop 0
	global_load_lds_dwordx4 v200, s[22:23]
	s_waitcnt vmcnt(32)
	s_waitcnt lgkmcnt(0)
	s_barrier
	s_setprio 1
	s_waitcnt lgkmcnt(0)
	v_mfma_f32_16x16x32_bf16 v[62:65], v[130:133], v[162:165], v[62:65]
	v_mfma_f32_16x16x32_bf16 v[58:61], v[138:141], v[162:165], v[58:61]
	v_mfma_f32_16x16x32_bf16 v[46:49], v[130:133], v[170:173], v[46:49]
	v_mfma_f32_16x16x32_bf16 v[42:45], v[138:141], v[170:173], v[42:45]
	v_mfma_f32_16x16x32_bf16 v[30:33], v[130:133], v[178:181], v[30:33]
	v_mfma_f32_16x16x32_bf16 v[26:29], v[138:141], v[178:181], v[26:29]
	v_mfma_f32_16x16x32_bf16 v[14:17], v[130:133], v[186:189], v[14:17]
	v_mfma_f32_16x16x32_bf16 v[10:13], v[138:141], v[186:189], v[10:13]
	v_mfma_f32_16x16x32_bf16 v[62:65], v[134:137], v[166:169], v[62:65]
	v_mfma_f32_16x16x32_bf16 v[58:61], v[142:145], v[166:169], v[58:61]
	v_mfma_f32_16x16x32_bf16 v[46:49], v[134:137], v[174:177], v[46:49]
	v_mfma_f32_16x16x32_bf16 v[42:45], v[142:145], v[174:177], v[42:45]
	v_mfma_f32_16x16x32_bf16 v[30:33], v[134:137], v[182:185], v[30:33]
	v_mfma_f32_16x16x32_bf16 v[26:29], v[142:145], v[182:185], v[26:29]
	v_mfma_f32_16x16x32_bf16 v[14:17], v[134:137], v[190:193], v[14:17]
	v_mfma_f32_16x16x32_bf16 v[10:13], v[142:145], v[190:193], v[10:13]
	s_setprio 0
	s_setprio 1
	v_mfma_f32_16x16x32_bf16 v[54:57], v[146:149], v[162:165], v[54:57]
	v_mfma_f32_16x16x32_bf16 v[50:53], v[154:157], v[162:165], v[50:53]
	v_mfma_f32_16x16x32_bf16 v[38:41], v[146:149], v[170:173], v[38:41]
	v_mfma_f32_16x16x32_bf16 v[34:37], v[154:157], v[170:173], v[34:37]
	v_mfma_f32_16x16x32_bf16 v[22:25], v[146:149], v[178:181], v[22:25]
	v_mfma_f32_16x16x32_bf16 v[18:21], v[154:157], v[178:181], v[18:21]
	v_mfma_f32_16x16x32_bf16 v[6:9], v[146:149], v[186:189], v[6:9]
	v_mfma_f32_16x16x32_bf16 v[2:5], v[154:157], v[186:189], v[2:5]
	v_mfma_f32_16x16x32_bf16 v[54:57], v[150:153], v[166:169], v[54:57]
	v_mfma_f32_16x16x32_bf16 v[50:53], v[158:161], v[166:169], v[50:53]
	v_mfma_f32_16x16x32_bf16 v[38:41], v[150:153], v[174:177], v[38:41]
	v_mfma_f32_16x16x32_bf16 v[34:37], v[158:161], v[174:177], v[34:37]
	v_mfma_f32_16x16x32_bf16 v[22:25], v[150:153], v[182:185], v[22:25]
	v_mfma_f32_16x16x32_bf16 v[18:21], v[158:161], v[182:185], v[18:21]
	v_mfma_f32_16x16x32_bf16 v[6:9], v[150:153], v[190:193], v[6:9]
	v_mfma_f32_16x16x32_bf16 v[2:5], v[158:161], v[190:193], v[2:5]
	s_setprio 0
	s_barrier
; #define PG8_STAGE(bufoff, gbase, voff) do { _Pragma("unroll") for (int _i = 0; _i < 2; ++_i) \
;         __builtin_amdgcn_global_load_lds((const unsigned*)((const char*)(gbase) + (voff)[_i]), (LAS unsigned*)(lds + (bufoff) + ldsw + _i * 8192), 16, 0, 0); } while (0)
; #define PG8_LDA(dst, b, h) do { _Pragma("unroll") for (int m = 0; m < 4; ++m) _Pragma("unroll") for (int k = 0; k < 2; ++k) dst[m][k] = *(const LAS bf16x8*)(lds + PG8_SA(b, h) + aoff + m * 2048 + k * 1024); } while (0)
; #define PG8_LDB(dst, b, h) do { _Pragma("unroll") for (int n = 0; n < 2; ++n) _Pragma("unroll") for (int k = 0; k < 2; ++k) dst[n][k] = *(const LAS bf16x8*)(lds + PG8_SB(b, h) + boff + n * 2048 + k * 1024); } while (0)
; #define PG8_MMA(ai, bj, At, Bt) do { __builtin_amdgcn_s_setprio(1); _Pragma("unroll") for (int m = 0; m < 4; ++m) _Pragma("unroll") for (int n = 0; n < 2; ++n) _Pragma("unroll") for (int k = 0; k < 2; ++k) \
;         acc[ai][bj][m][n] = __builtin_amdgcn_mfma_f32_16x16x32_bf16(Bt[n][k], At[m][k], acc[ai][bj][m][n], 0, 0, 0); __builtin_amdgcn_s_setprio(0); } while (0)
; #define PG8_WAIT_V(n) asm volatile("s_waitcnt vmcnt(" #n ")" ::: "memory")
; #define PG8_WAIT_L(n) asm volatile("s_waitcnt lgkmcnt(" #n ")" ::: "memory")
; #define PG8_BAR __builtin_amdgcn_s_barrier()
; #define PG8_SCHED __builtin_amdgcn_sched_barrier(0)
; template <class Epi, class Sched, int KC, bool ALIGN_EPI = false, bool SP2 = false, bool ATILED = false>
; __device__ __forceinline__ void gemm_phase(LAS unsigned char* lds, const Gemm g, const Sched& S, const Epi& E, int wave_s) {
;     ...
;             PG8_LDB(B0, 1, 0); PG8_LDB(B1, 1, 1); PG8_SCHED; PG8_LDA(At, 1, 0); PG8_STAGE(PG8_SA(0, 1), a2 + hstepA, voffA);
;             PG8_WAIT_V(8); PG8_WAIT_L(0); PG8_BAR; PG8_MMA(0, 0, At, B0); PG8_MMA(0, 1, At, B1); PG8_BAR; PG8_SCHED;
;             PG8_LDA(At, 1, 1); PG8_STAGE(PG8_SB(1, 0), b3, voffB); PG8_STAGE(PG8_SB(1, 1), b3 + hstepB, voffB); PG8_STAGE(PG8_SA(1, 0), a3, voffA);
;             PG8_WAIT_V(8); PG8_WAIT_L(0); PG8_BAR; PG8_MMA(1, 0, At, B0); PG8_MMA(1, 1, At, B1); PG8_BAR; PG8_SCHED;
	s_add_i32 s49, 0, 0x18000
	s_add_i32 s50, 0, 0x1c000
	v_add_u32_e32 v142, s49, v229
	v_add_u32_e32 v158, s50, v229
	ds_read_b128 v[130:133], v142
	ds_read_b128 v[134:137], v142 offset:1024
	ds_read_b128 v[138:141], v142 offset:2048
	ds_read_b128 v[142:145], v142 offset:3072
	ds_read_b128 v[146:149], v158
	ds_read_b128 v[150:153], v158 offset:1024
	ds_read_b128 v[154:157], v158 offset:2048
	ds_read_b128 v[158:161], v158 offset:3072
	s_add_u32 s22, s22, 0x80000
	s_addc_u32 s23, s23, 0
	s_mov_b32 m0, s36
	ds_read_b128 v[162:165], v230 offset:32768
	ds_read_b128 v[166:169], v230 offset:33792
	ds_read_b128 v[170:173], v230 offset:34816
	ds_read_b128 v[174:177], v230 offset:35840
	ds_read_b128 v[178:181], v230 offset:36864
	ds_read_b128 v[182:185], v230 offset:37888
	ds_read_b128 v[186:189], v230 offset:38912
	ds_read_b128 v[190:193], v230 offset:39936
	global_load_lds_dwordx4 v198, s[22:23]
	s_mov_b32 m0, s37
	s_nop 0
	global_load_lds_dwordx4 v200, s[22:23]
	s_waitcnt vmcnt(8)
	s_waitcnt lgkmcnt(0)
	s_barrier
	s_setprio 1
	s_waitcnt lgkmcnt(0)
	v_mfma_f32_16x16x32_bf16 v[126:129], v[130:133], v[162:165], v[126:129]
	v_mfma_f32_16x16x32_bf16 v[122:125], v[138:141], v[162:165], v[122:125]
	v_mfma_f32_16x16x32_bf16 v[110:113], v[130:133], v[170:173], v[110:113]
	v_mfma_f32_16x16x32_bf16 v[106:109], v[138:141], v[170:173], v[106:109]
	v_mfma_f32_16x16x32_bf16 v[94:97], v[130:133], v[178:181], v[94:97]
	v_mfma_f32_16x16x32_bf16 v[90:93], v[138:141], v[178:181], v[90:93]
	v_mfma_f32_16x16x32_bf16 v[78:81], v[130:133], v[186:189], v[78:81]
	v_mfma_f32_16x16x32_bf16 v[74:77], v[138:141], v[186:189], v[74:77]
	v_mfma_f32_16x16x32_bf16 v[126:129], v[134:137], v[166:169], v[126:129]
	v_mfma_f32_16x16x32_bf16 v[122:125], v[142:145], v[166:169], v[122:125]
	v_mfma_f32_16x16x32_bf16 v[110:113], v[134:137], v[174:177], v[110:113]
	v_mfma_f32_16x16x32_bf16 v[106:109], v[142:145], v[174:177], v[106:109]
	v_mfma_f32_16x16x32_bf16 v[94:97], v[134:137], v[182:185], v[94:97]
	v_mfma_f32_16x16x32_bf16 v[90:93], v[142:145], v[182:185], v[90:93]
	v_mfma_f32_16x16x32_bf16 v[78:81], v[134:137], v[190:193], v[78:81]
	v_mfma_f32_16x16x32_bf16 v[74:77], v[142:145], v[190:193], v[74:77]
	s_setprio 0
	s_setprio 1
	v_mfma_f32_16x16x32_bf16 v[118:121], v[146:149], v[162:165], v[118:121]
	v_mfma_f32_16x16x32_bf16 v[114:117], v[154:157], v[162:165], v[114:117]
	v_mfma_f32_16x16x32_bf16 v[102:105], v[146:149], v[170:173], v[102:105]
	v_mfma_f32_16x16x32_bf16 v[98:101], v[154:157], v[170:173], v[98:101]
	v_mfma_f32_16x16x32_bf16 v[86:89], v[146:149], v[178:181], v[86:89]
	v_mfma_f32_16x16x32_bf16 v[82:85], v[154:157], v[178:181], v[82:85]
	v_mfma_f32_16x16x32_bf16 v[70:73], v[146:149], v[186:189], v[70:73]
	v_mfma_f32_16x16x32_bf16 v[66:69], v[154:157], v[186:189], v[66:69]
	v_mfma_f32_16x16x32_bf16 v[118:121], v[150:153], v[166:169], v[118:121]
	v_mfma_f32_16x16x32_bf16 v[114:117], v[158:161], v[166:169], v[114:117]
	v_mfma_f32_16x16x32_bf16 v[102:105], v[150:153], v[174:177], v[102:105]
	v_mfma_f32_16x16x32_bf16 v[98:101], v[158:161], v[174:177], v[98:101]
	v_mfma_f32_16x16x32_bf16 v[86:89], v[150:153], v[182:185], v[86:89]
	v_mfma_f32_16x16x32_bf16 v[82:85], v[158:161], v[182:185], v[82:85]
	v_mfma_f32_16x16x32_bf16 v[70:73], v[150:153], v[190:193], v[70:73]
	v_mfma_f32_16x16x32_bf16 v[66:69], v[158:161], v[190:193], v[66:69]
	s_setprio 0
	s_barrier
	s_add_u32 s98, s20, 0x80
	s_addc_u32 s99, s21, 0
	s_add_i32 s22, s49, s31
	s_mov_b32 m0, s22
	ds_read_b128 v[162:165], v230 offset:49152
	ds_read_b128 v[166:169], v230 offset:50176
	ds_read_b128 v[170:173], v230 offset:51200
	ds_read_b128 v[174:177], v230 offset:52224
	ds_read_b128 v[178:181], v230 offset:53248
	ds_read_b128 v[182:185], v230 offset:54272
	ds_read_b128 v[186:189], v230 offset:55296
	ds_read_b128 v[190:193], v230 offset:56320
	global_load_lds_dwordx4 v0, s[98:99]
	s_add_i32 m0, s22, 0x2000
	s_add_u32 s20, s20, 0x20080
	s_addc_u32 s21, s21, 0
	s_add_i32 s22, s50, s31
	global_load_lds_dwordx4 v202, s[98:99]
	s_mov_b32 m0, s22
	s_nop 0
	global_load_lds_dwordx4 v0, s[20:21]
	s_add_i32 m0, s22, 0x2000
	s_nop 0
	global_load_lds_dwordx4 v202, s[20:21]
	s_mov_b32 m0, s41
	s_nop 0
	global_load_lds_dwordx4 v198, s[100:101]
	s_mov_b32 m0, s42
	s_nop 0
	global_load_lds_dwordx4 v200, s[100:101]
	s_waitcnt vmcnt(8)
	s_waitcnt lgkmcnt(0)
	s_barrier
	s_setprio 1
	s_waitcnt lgkmcnt(0)
	v_mfma_f32_16x16x32_bf16 v[62:65], v[130:133], v[162:165], v[62:65]
	v_mfma_f32_16x16x32_bf16 v[58:61], v[138:141], v[162:165], v[58:61]
	v_mfma_f32_16x16x32_bf16 v[46:49], v[130:133], v[170:173], v[46:49]
	v_mfma_f32_16x16x32_bf16 v[42:45], v[138:141], v[170:173], v[42:45]
	v_mfma_f32_16x16x32_bf16 v[30:33], v[130:133], v[178:181], v[30:33]
	v_mfma_f32_16x16x32_bf16 v[26:29], v[138:141], v[178:181], v[26:29]
	v_mfma_f32_16x16x32_bf16 v[14:17], v[130:133], v[186:189], v[14:17]
	v_mfma_f32_16x16x32_bf16 v[10:13], v[138:141], v[186:189], v[10:13]
	v_mfma_f32_16x16x32_bf16 v[62:65], v[134:137], v[166:169], v[62:65]
	v_mfma_f32_16x16x32_bf16 v[58:61], v[142:145], v[166:169], v[58:61]
	v_mfma_f32_16x16x32_bf16 v[46:49], v[134:137], v[174:177], v[46:49]
	v_mfma_f32_16x16x32_bf16 v[42:45], v[142:145], v[174:177], v[42:45]
	v_mfma_f32_16x16x32_bf16 v[30:33], v[134:137], v[182:185], v[30:33]
	v_mfma_f32_16x16x32_bf16 v[26:29], v[142:145], v[182:185], v[26:29]
	v_mfma_f32_16x16x32_bf16 v[14:17], v[134:137], v[190:193], v[14:17]
	v_mfma_f32_16x16x32_bf16 v[10:13], v[142:145], v[190:193], v[10:13]
	s_setprio 0
	s_setprio 1
	v_mfma_f32_16x16x32_bf16 v[54:57], v[146:149], v[162:165], v[54:57]
	v_mfma_f32_16x16x32_bf16 v[50:53], v[154:157], v[162:165], v[50:53]
	v_mfma_f32_16x16x32_bf16 v[38:41], v[146:149], v[170:173], v[38:41]
	v_mfma_f32_16x16x32_bf16 v[34:37], v[154:157], v[170:173], v[34:37]
	v_mfma_f32_16x16x32_bf16 v[22:25], v[146:149], v[178:181], v[22:25]
	v_mfma_f32_16x16x32_bf16 v[18:21], v[154:157], v[178:181], v[18:21]
	v_mfma_f32_16x16x32_bf16 v[6:9], v[146:149], v[186:189], v[6:9]
	v_mfma_f32_16x16x32_bf16 v[2:5], v[154:157], v[186:189], v[2:5]
	v_mfma_f32_16x16x32_bf16 v[54:57], v[150:153], v[166:169], v[54:57]
	v_mfma_f32_16x16x32_bf16 v[50:53], v[158:161], v[166:169], v[50:53]
	v_mfma_f32_16x16x32_bf16 v[38:41], v[150:153], v[174:177], v[38:41]
	v_mfma_f32_16x16x32_bf16 v[34:37], v[158:161], v[174:177], v[34:37]
	v_mfma_f32_16x16x32_bf16 v[22:25], v[150:153], v[182:185], v[22:25]
	v_mfma_f32_16x16x32_bf16 v[18:21], v[158:161], v[182:185], v[18:21]
	v_mfma_f32_16x16x32_bf16 v[6:9], v[150:153], v[190:193], v[6:9]
	v_mfma_f32_16x16x32_bf16 v[2:5], v[158:161], v[190:193], v[2:5]
	s_setprio 0
	s_barrier
	s_add_i32 s48, s48, 2
	s_add_u32 s46, s46, 0x100
	s_addc_u32 s47, s47, 0
	s_add_u32 s18, s18, 0x100
	s_addc_u32 s19, s19, 0
	s_cmp_gt_u32 s48, 29
